# PLE epilogue hand-scheduled: rstd from LDS table (table also built in the E/PLE phase), loads of all 8 row groups run ahead into dead accumulators, reduction overlapped
# baseline (speedup 1.0000x reference)
; __device__ __forceinline__ void epi_run(const Epi& E, f32x4 (&acc)[2][2][4][2], const Unit& u, int wr, int wc, int fr, int fq) {
;     const int mode = u.mode;
;     const int row0 = u.pm * 256 + wr * 64 + fr, col0 = u.pn * 256 + wc * 32 + 8 * fq;
;     if (mode == MODE_IN || mode == MODE_UP) {
;         float rs[2][4]; epi_rstd(E.ssq_in, row0, fq, rs);
;     ...
;     } else {
;         float rs[2][4]; epi_rstd(E.ssq_in, row0, fq, rs);
.LBB0_256:
	v_readlane_b32 s12, v250, 13
	s_mov_b32 s13, -1
	s_cmp_eq_u32 s12, 0
	s_cbranch_scc1 .Lmy_tab_yes
	s_cmp_eq_u32 s12, 5
	s_cbranch_scc1 .Lmy_tab_yes
	s_cmp_eq_u32 s12, 6
	s_cbranch_scc1 .Lmy_tab_yes
	v_writelane_b32 v250, s13, 41
	s_branch .Lmy_tab_done

; __device__ __forceinline__ void epi_rstd(const float* ssq, int row0, int fq, float (&rs)[2][4]) {
;     float part[2][4][4];
; #pragma unroll
;     for (int ai = 0; ai < 2; ++ai)
; #pragma unroll
;         for (int m = 0; m < 4; ++m)
; #pragma unroll
;             for (int j = 0; j < 4; ++j) part[ai][m][j] = ssq[(size_t)(4 * fq + j) * M + row0 + ai * 128 + m * 16];
; #pragma unroll
;     for (int ai = 0; ai < 2; ++ai)
; #pragma unroll
;         for (int m = 0; m < 4; ++m) { float t = (part[ai][m][0] + part[ai][m][1]) + (part[ai][m][2] + part[ai][m][3]); t += __shfl_xor(t, 16); t += __shfl_xor(t, 32); rs[ai][m] = __builtin_amdgcn_rsqf(t * (1.0f / 1024.0f) + EPS); }
; }
; __device__ __forceinline__ void epi_run(const Epi& E, f32x4 (&acc)[2][2][4][2], const Unit& u, int wr, int wc, int fr, int fq) {
;     ...
;     } else {
;         float rs[2][4]; epi_rstd(E.ssq_in, row0, fq, rs);
;         float* sslot = E.ssq_out + (size_t)(u.pn * 4 + wc) * M;
; #pragma unroll
;         for (int ai = 0; ai < 2; ++ai)
; #pragma unroll
;             for (int mh = 0; mh < 2; ++mh) { u32x4 x[2][2], c[2][2];
; #pragma unroll
;                 for (int mm = 0; mm < 2; ++mm)
; #pragma unroll
;                     for (int bj = 0; bj < 2; ++bj) { const size_t off = (size_t)(row0 + ai * 128 + (2 * mh + mm) * 16) * D + col0 + bj * 128; x[mm][bj] = *(const u32x4*)(E.xin16 + off); c[mm][bj] = *(const u32x4*)(E.C16 + off); }
.LBB0_308:
	s_and_b64 vcc, exec, s[96:97]
	s_cbranch_vccz .LBB0_326
	v_readlane_b32 s8, v250, 41
	s_nop 0
	s_cmp_eq_u32 s8, s95
	s_cbranch_scc1 .Lmy_ple_fast
	v_readlane_b32 s8, v250, 3
	v_readlane_b32 s9, v250, 4
	v_and_b32_e32 v146, 0xff, v195
	v_lshl_add_u32 v146, s95, 8, v146
	v_lshlrev_b32_e32 v146, 2, v146
	s_nop 3
	global_load_dword v130, v146, s[8:9]
	v_add_u32_e32 v147, 0x10000, v146
	global_load_dword v131, v147, s[8:9]
	v_add_u32_e32 v147, 0x20000, v146
	global_load_dword v132, v147, s[8:9]
	v_add_u32_e32 v147, 0x30000, v146
	global_load_dword v133, v147, s[8:9]
	v_add_u32_e32 v147, 0x40000, v146
	global_load_dword v134, v147, s[8:9]
	v_add_u32_e32 v147, 0x50000, v146
	global_load_dword v135, v147, s[8:9]
	v_add_u32_e32 v147, 0x60000, v146
	global_load_dword v136, v147, s[8:9]
	v_add_u32_e32 v147, 0x70000, v146
	global_load_dword v137, v147, s[8:9]
	v_add_u32_e32 v147, 0x80000, v146
	global_load_dword v138, v147, s[8:9]
	v_add_u32_e32 v147, 0x90000, v146
	global_load_dword v139, v147, s[8:9]
	v_add_u32_e32 v147, 0xa0000, v146
	global_load_dword v140, v147, s[8:9]
	v_add_u32_e32 v147, 0xb0000, v146
	global_load_dword v141, v147, s[8:9]
	v_add_u32_e32 v147, 0xc0000, v146
	global_load_dword v142, v147, s[8:9]
	v_add_u32_e32 v147, 0xd0000, v146
	global_load_dword v143, v147, s[8:9]
	v_add_u32_e32 v147, 0xe0000, v146
	global_load_dword v144, v147, s[8:9]
	v_add_u32_e32 v147, 0xf0000, v146
	global_load_dword v145, v147, s[8:9]
	s_waitcnt vmcnt(0)
	v_add_f32_e32 v130, v130, v131
	v_add_f32_e32 v132, v132, v133
	v_add_f32_e32 v130, v130, v132
	v_add_f32_e32 v134, v134, v135
	v_add_f32_e32 v136, v136, v137
	v_add_f32_e32 v134, v134, v136
	v_add_f32_e32 v138, v138, v139
	v_add_f32_e32 v140, v140, v141
	v_add_f32_e32 v138, v138, v140
	v_add_f32_e32 v142, v142, v143
	v_add_f32_e32 v144, v144, v145
	v_add_f32_e32 v142, v142, v144
	v_add_f32_e32 v130, v130, v134
	v_add_f32_e32 v138, v138, v142
	v_add_f32_e32 v130, v130, v138
	v_fmamk_f32 v130, v130, 0x3a800000, v197
	v_rsq_f32_e32 v130, v130
	v_and_b32_e32 v147, 0xff, v195
	v_lshlrev_b32_e32 v147, 2, v147
	v_add_u32_e32 v147, 0x20800, v147
	ds_write_b32 v147, v130
	v_writelane_b32 v250, s95, 41
	s_waitcnt lgkmcnt(0)
	s_barrier
.Lmy_ple_fast:
	v_ashrrev_i32_e32 v211, 31, v210
	v_ashrrev_i32_e32 v213, 31, v212
	v_lshlrev_b32_e32 v0, 2, v239
	v_add_u32_e32 v0, 0x20800, v0
	ds_read_b32 v214, v0
	ds_read_b32 v215, v0 offset:64
	ds_read_b32 v216, v0 offset:128
	ds_read_b32 v217, v0 offset:192
	ds_read_b32 v218, v0 offset:512
	ds_read_b32 v219, v0 offset:576
	ds_read_b32 v220, v0 offset:640
	ds_read_b32 v221, v0 offset:704
	v_lshlrev_b64 v[182:183], 11, v[210:211]
	v_lshlrev_b64 v[184:185], 1, v[212:213]
	v_lshl_add_u64 v[182:183], v[182:183], 0, v[184:185]
	v_lshl_add_u64 v[184:185], s[62:63], 0, v[182:183]
	v_lshl_add_u64 v[186:187], s[78:79], 0, v[182:183]
	v_lshl_add_u64 v[182:183], s[48:49], 0, v[182:183]
	global_load_dwordx4 v[130:133], v[182:183], off
	global_load_dwordx4 v[134:137], v[184:185], off
	global_load_dwordx4 v[138:141], v[182:183], off offset:256
	global_load_dwordx4 v[142:145], v[184:185], off offset:256
	s_mov_b64 s[20:21], 0x8000
	v_lshl_add_u64 v[188:189], v[182:183], 0, s[20:21]
	v_lshl_add_u64 v[190:191], v[184:185], 0, s[20:21]
	global_load_dwordx4 v[146:149], v[188:189], off
	global_load_dwordx4 v[150:153], v[190:191], off
	global_load_dwordx4 v[154:157], v[188:189], off offset:256
	global_load_dwordx4 v[158:161], v[190:191], off offset:256
	v_lshrrev_b32_e32 v170, 2, v201
	v_and_b32_e32 v171, 3, v201
	v_lshl_add_u32 v223, v171, 4, v170
	v_lshlrev_b32_e32 v223, 2, v223
	v_and_b32_e32 v172, 15, v201
	v_sub_u32_e32 v170, v170, v172
	v_lshrrev_b32_e32 v172, 4, v201
	v_sub_u32_e32 v171, v171, v172
	v_lshlrev_b32_e32 v171, 4, v171
	v_lshl_add_u32 v226, v170, 11, v171
	v_ashrrev_i32_e32 v227, 31, v226
	v_lshl_add_u64 v[186:187], v[186:187], 0, v[226:227]
	v_xor_b32_e32 v224, 16, v201
	v_xor_b32_e32 v225, 32, v201
	v_lshlrev_b32_e32 v224, 2, v224
	v_lshlrev_b32_e32 v225, 2, v225
	v_mov_b32_e32 v222, 1.0
	s_lshl_b32 s2, s23, 2
	v_readlane_b32 s8, v250, 29
	s_nop 0
	s_or_b32 s8, s2, s8
	s_ashr_i32 s9, s8, 31
	s_lshl_b64 s[8:9], s[8:9], 16
	s_add_u32 s44, s76, s8
	s_addc_u32 s45, s77, s9
	v_lshl_add_u64 v[192:193], v[210:211], 2, s[44:45]
	s_waitcnt lgkmcnt(0)
	v_mul_f32_e32 v214, 0xbfb8aa3b, v214
	v_mul_f32_e32 v215, 0xbfb8aa3b, v215
	v_mul_f32_e32 v216, 0xbfb8aa3b, v216
	v_mul_f32_e32 v217, 0xbfb8aa3b, v217
	v_mul_f32_e32 v218, 0xbfb8aa3b, v218
	v_mul_f32_e32 v219, 0xbfb8aa3b, v219
	v_mul_f32_e32 v220, 0xbfb8aa3b, v220
	v_mul_f32_e32 v221, 0xbfb8aa3b, v221
	s_waitcnt vmcnt(4)
; __device__ __forceinline__ float bf_lo(unsigned w) { return __uint_as_float(w << 16); }
; __device__ __forceinline__ float bf_hi(unsigned w) { return __uint_as_float(w & 0xffff0000u); }
; __device__ __forceinline__ float sigm(float v) { return __builtin_amdgcn_rcpf(1.0f + __builtin_amdgcn_exp2f(-1.44269504089f * v)); }
; __device__ __forceinline__ u32x4 pack8(const f32x4& v0, const f32x4& v1) { u32x4 w; w.x = cvt_pk_bf16(v0[0], v0[1]); w.y = cvt_pk_bf16(v0[2], v0[3]); w.z = cvt_pk_bf16(v1[0], v1[1]); w.w = cvt_pk_bf16(v1[2], v1[3]); return w; }
; __device__ __forceinline__ float sumsq8(const f32x4& v0, const f32x4& v1) { return (v0[0] * v0[0] + v0[1] * v0[1]) + (v0[2] * v0[2] + v0[3] * v0[3]) + (v1[0] * v1[0] + v1[1] * v1[1]) + (v1[2] * v1[2] + v1[3] * v1[3]); }
; __device__ __forceinline__ void epi_run(const Epi& E, f32x4 (&acc)[2][2][4][2], const Unit& u, int wr, int wc, int fr, int fq) {
;     ...
;                 for (int mm = 0; mm < 2; ++mm) { const int m = 2 * mh + mm, row = row0 + ai * 128 + m * 16; float sq = 0.f;
; #pragma unroll
;                     for (int bj = 0; bj < 2; ++bj) { const u32x4 xx = x[mm][bj], cc = c[mm][bj];
;                         const f32x4 c0 = (f32x4){bf_lo(cc.x), bf_hi(cc.x), bf_lo(cc.y), bf_hi(cc.y)}, c1 = (f32x4){bf_lo(cc.z), bf_hi(cc.z), bf_lo(cc.w), bf_hi(cc.w)};
;                         f32x4 v0 = acc[ai][bj][m][0] * rs[ai][m], v1 = acc[ai][bj][m][1] * rs[ai][m];
; #pragma unroll
;                         for (int e = 0; e < 4; ++e) { v0[e] = sigm(v0[e]) * c0[e]; v1[e] = sigm(v1[e]) * c1[e]; }
;                         const f32x4 x0 = (f32x4){bf_lo(xx.x), bf_hi(xx.x), bf_lo(xx.y), bf_hi(xx.y)} + v0, x1 = (f32x4){bf_lo(xx.z), bf_hi(xx.z), bf_lo(xx.w), bf_hi(xx.w)} + v1;
;                         sq += sumsq8(x0, x1); *(u32x4*)(E.xout16 + (size_t)row * D + col0 + bj * 128) = pack8(x0, x1); }
;                     sq += __shfl_xor(sq, 16); sq += __shfl_xor(sq, 32); if (fq == 0) sslot[row] = sq; }
	v_mov_b32_e32 v243, 0
	v_mov_b32_e32 v249, 0
	v_pk_mul_f32 v[170:171], v[126:127], v[214:215] op_sel_hi:[1,0]
	v_pk_mul_f32 v[172:173], v[128:129], v[214:215] op_sel_hi:[1,0]
	v_pk_mul_f32 v[174:175], v[122:123], v[214:215] op_sel_hi:[1,0]
	v_pk_mul_f32 v[176:177], v[124:125], v[214:215] op_sel_hi:[1,0]
	v_exp_f32_e32 v170, v170
	v_exp_f32_e32 v171, v171
	v_exp_f32_e32 v172, v172
	v_exp_f32_e32 v173, v173
	v_exp_f32_e32 v174, v174
	v_exp_f32_e32 v175, v175
	v_exp_f32_e32 v176, v176
	v_exp_f32_e32 v177, v177
	v_pk_add_f32 v[170:171], v[170:171], v[222:223] op_sel_hi:[1,0]
	v_pk_add_f32 v[172:173], v[172:173], v[222:223] op_sel_hi:[1,0]
	v_pk_add_f32 v[174:175], v[174:175], v[222:223] op_sel_hi:[1,0]
	v_pk_add_f32 v[176:177], v[176:177], v[222:223] op_sel_hi:[1,0]
	v_rcp_f32_e32 v170, v170
	v_rcp_f32_e32 v171, v171
	v_rcp_f32_e32 v172, v172
	v_rcp_f32_e32 v173, v173
	v_rcp_f32_e32 v174, v174
	v_rcp_f32_e32 v175, v175
	v_rcp_f32_e32 v176, v176
	v_rcp_f32_e32 v177, v177
	v_lshlrev_b32_e32 v178, 16, v134
	v_and_b32_e32 v179, 0xffff0000, v134
	v_lshlrev_b32_e32 v180, 16, v130
	v_and_b32_e32 v181, 0xffff0000, v130
	v_pk_fma_f32 v[170:171], v[170:171], v[178:179], v[180:181]
	v_lshlrev_b32_e32 v178, 16, v135
	v_and_b32_e32 v179, 0xffff0000, v135
	v_lshlrev_b32_e32 v180, 16, v131
	v_and_b32_e32 v181, 0xffff0000, v131
	v_pk_fma_f32 v[172:173], v[172:173], v[178:179], v[180:181]
	v_fmac_f32_e32 v243, v170, v170
	v_fmac_f32_e32 v249, v171, v171
	v_cvt_pk_bf16_f32 v166, v170, v171
	v_lshlrev_b32_e32 v178, 16, v136
	v_and_b32_e32 v179, 0xffff0000, v136
	v_lshlrev_b32_e32 v180, 16, v132
	v_and_b32_e32 v181, 0xffff0000, v132
	v_pk_fma_f32 v[174:175], v[174:175], v[178:179], v[180:181]
	v_fmac_f32_e32 v243, v172, v172
	v_fmac_f32_e32 v249, v173, v173
	v_cvt_pk_bf16_f32 v167, v172, v173
	v_lshlrev_b32_e32 v178, 16, v137
	v_and_b32_e32 v179, 0xffff0000, v137
	v_lshlrev_b32_e32 v180, 16, v133
	v_and_b32_e32 v181, 0xffff0000, v133
	v_pk_fma_f32 v[176:177], v[176:177], v[178:179], v[180:181]
	v_fmac_f32_e32 v243, v174, v174
	v_fmac_f32_e32 v249, v175, v175
	v_cvt_pk_bf16_f32 v168, v174, v175
	v_fmac_f32_e32 v243, v176, v176
	v_fmac_f32_e32 v249, v177, v177
	v_cvt_pk_bf16_f32 v169, v176, v177
	v_mov_b64_e32 v[228:229], v[186:187]
	ds_bpermute_b32 v244, v223, v166
	ds_bpermute_b32 v245, v223, v167
	ds_bpermute_b32 v246, v223, v168
	ds_bpermute_b32 v247, v223, v169
	v_pk_mul_f32 v[170:171], v[118:119], v[214:215] op_sel_hi:[1,0]
	v_pk_mul_f32 v[172:173], v[120:121], v[214:215] op_sel_hi:[1,0]
	v_pk_mul_f32 v[174:175], v[114:115], v[214:215] op_sel_hi:[1,0]
	v_pk_mul_f32 v[176:177], v[116:117], v[214:215] op_sel_hi:[1,0]
	v_exp_f32_e32 v170, v170
	v_exp_f32_e32 v171, v171
	v_exp_f32_e32 v172, v172
	v_exp_f32_e32 v173, v173
	v_exp_f32_e32 v174, v174
	v_exp_f32_e32 v175, v175
	v_exp_f32_e32 v176, v176
	v_exp_f32_e32 v177, v177
	v_pk_add_f32 v[170:171], v[170:171], v[222:223] op_sel_hi:[1,0]
	v_pk_add_f32 v[172:173], v[172:173], v[222:223] op_sel_hi:[1,0]
	v_pk_add_f32 v[174:175], v[174:175], v[222:223] op_sel_hi:[1,0]
	v_pk_add_f32 v[176:177], v[176:177], v[222:223] op_sel_hi:[1,0]
	v_rcp_f32_e32 v170, v170
	v_rcp_f32_e32 v171, v171
	v_rcp_f32_e32 v172, v172
	v_rcp_f32_e32 v173, v173
	v_rcp_f32_e32 v174, v174
	v_rcp_f32_e32 v175, v175
	v_rcp_f32_e32 v176, v176
	v_rcp_f32_e32 v177, v177
	v_lshlrev_b32_e32 v178, 16, v142
	v_and_b32_e32 v179, 0xffff0000, v142
	v_lshlrev_b32_e32 v180, 16, v138
	v_and_b32_e32 v181, 0xffff0000, v138
	v_pk_fma_f32 v[170:171], v[170:171], v[178:179], v[180:181]
	v_lshlrev_b32_e32 v178, 16, v143
	v_and_b32_e32 v179, 0xffff0000, v143
	v_lshlrev_b32_e32 v180, 16, v139
	v_and_b32_e32 v181, 0xffff0000, v139
	v_pk_fma_f32 v[172:173], v[172:173], v[178:179], v[180:181]
	v_fmac_f32_e32 v243, v170, v170
	v_fmac_f32_e32 v249, v171, v171
	v_cvt_pk_bf16_f32 v166, v170, v171
	v_lshlrev_b32_e32 v178, 16, v144
	v_and_b32_e32 v179, 0xffff0000, v144
	v_lshlrev_b32_e32 v180, 16, v140
	v_and_b32_e32 v181, 0xffff0000, v140
	v_pk_fma_f32 v[174:175], v[174:175], v[178:179], v[180:181]
	v_fmac_f32_e32 v243, v172, v172
	v_fmac_f32_e32 v249, v173, v173
	v_cvt_pk_bf16_f32 v167, v172, v173
	v_lshlrev_b32_e32 v178, 16, v145
	v_and_b32_e32 v179, 0xffff0000, v145
	v_lshlrev_b32_e32 v180, 16, v141
	v_and_b32_e32 v181, 0xffff0000, v141
	v_pk_fma_f32 v[176:177], v[176:177], v[178:179], v[180:181]
	v_fmac_f32_e32 v243, v174, v174
	v_fmac_f32_e32 v249, v175, v175
	v_cvt_pk_bf16_f32 v168, v174, v175
	v_fmac_f32_e32 v243, v176, v176
	v_fmac_f32_e32 v249, v177, v177
	v_cvt_pk_bf16_f32 v169, v176, v177
	s_waitcnt lgkmcnt(0)
	global_store_dwordx4 v[228:229], v[244:247], off
	ds_bpermute_b32 v162, v223, v166
	ds_bpermute_b32 v163, v223, v167
	ds_bpermute_b32 v164, v223, v168
	ds_bpermute_b32 v165, v223, v169
	v_add_f32_e32 v243, v243, v249
	ds_bpermute_b32 v0, v224, v243
	s_mov_b64 s[20:21], 0x10000
	v_lshl_add_u64 v[188:189], v[182:183], 0, s[20:21]
	v_lshl_add_u64 v[190:191], v[184:185], 0, s[20:21]
	global_load_dwordx4 v[126:129], v[188:189], off
	global_load_dwordx4 v[122:125], v[190:191], off
	global_load_dwordx4 v[118:121], v[188:189], off offset:256
	global_load_dwordx4 v[114:117], v[190:191], off offset:256
	s_mov_b64 s[20:21], 0x18000
	v_lshl_add_u64 v[188:189], v[182:183], 0, s[20:21]
	v_lshl_add_u64 v[190:191], v[184:185], 0, s[20:21]
	global_load_dwordx4 v[130:133], v[188:189], off
	global_load_dwordx4 v[134:137], v[190:191], off
	global_load_dwordx4 v[138:141], v[188:189], off offset:256
	global_load_dwordx4 v[142:145], v[190:191], off offset:256
	s_waitcnt vmcnt(9)
; __device__ __forceinline__ float bf_lo(unsigned w) { return __uint_as_float(w << 16); }
; __device__ __forceinline__ float bf_hi(unsigned w) { return __uint_as_float(w & 0xffff0000u); }
; __device__ __forceinline__ float sigm(float v) { return __builtin_amdgcn_rcpf(1.0f + __builtin_amdgcn_exp2f(-1.44269504089f * v)); }
; __device__ __forceinline__ u32x4 pack8(const f32x4& v0, const f32x4& v1) { u32x4 w; w.x = cvt_pk_bf16(v0[0], v0[1]); w.y = cvt_pk_bf16(v0[2], v0[3]); w.z = cvt_pk_bf16(v1[0], v1[1]); w.w = cvt_pk_bf16(v1[2], v1[3]); return w; }
; __device__ __forceinline__ float sumsq8(const f32x4& v0, const f32x4& v1) { return (v0[0] * v0[0] + v0[1] * v0[1]) + (v0[2] * v0[2] + v0[3] * v0[3]) + (v1[0] * v1[0] + v1[1] * v1[1]) + (v1[2] * v1[2] + v1[3] * v1[3]); }
; __device__ __forceinline__ void epi_run(const Epi& E, f32x4 (&acc)[2][2][4][2], const Unit& u, int wr, int wc, int fr, int fq) {
;     ...
;                 for (int mm = 0; mm < 2; ++mm) { const int m = 2 * mh + mm, row = row0 + ai * 128 + m * 16; float sq = 0.f;
; #pragma unroll
;                     for (int bj = 0; bj < 2; ++bj) { const u32x4 xx = x[mm][bj], cc = c[mm][bj];
;                         const f32x4 c0 = (f32x4){bf_lo(cc.x), bf_hi(cc.x), bf_lo(cc.y), bf_hi(cc.y)}, c1 = (f32x4){bf_lo(cc.z), bf_hi(cc.z), bf_lo(cc.w), bf_hi(cc.w)};
;                         f32x4 v0 = acc[ai][bj][m][0] * rs[ai][m], v1 = acc[ai][bj][m][1] * rs[ai][m];
; #pragma unroll
;                         for (int e = 0; e < 4; ++e) { v0[e] = sigm(v0[e]) * c0[e]; v1[e] = sigm(v1[e]) * c1[e]; }
;                         const f32x4 x0 = (f32x4){bf_lo(xx.x), bf_hi(xx.x), bf_lo(xx.y), bf_hi(xx.y)} + v0, x1 = (f32x4){bf_lo(xx.z), bf_hi(xx.z), bf_lo(xx.w), bf_hi(xx.w)} + v1;
;                         sq += sumsq8(x0, x1); *(u32x4*)(E.xout16 + (size_t)row * D + col0 + bj * 128) = pack8(x0, x1); }
;                     sq += __shfl_xor(sq, 16); sq += __shfl_xor(sq, 32); if (fq == 0) sslot[row] = sq; }
	v_mov_b32_e32 v248, 0
	v_mov_b32_e32 v249, 0
	v_pk_mul_f32 v[170:171], v[110:111], v[214:215] op_sel:[0,1] op_sel_hi:[1,1]
	v_pk_mul_f32 v[172:173], v[112:113], v[214:215] op_sel:[0,1] op_sel_hi:[1,1]
	v_pk_mul_f32 v[174:175], v[106:107], v[214:215] op_sel:[0,1] op_sel_hi:[1,1]
	v_pk_mul_f32 v[176:177], v[108:109], v[214:215] op_sel:[0,1] op_sel_hi:[1,1]
	v_exp_f32_e32 v170, v170
	v_exp_f32_e32 v171, v171
	v_exp_f32_e32 v172, v172
	v_exp_f32_e32 v173, v173
	v_exp_f32_e32 v174, v174
	v_exp_f32_e32 v175, v175
	v_exp_f32_e32 v176, v176
	v_exp_f32_e32 v177, v177
	v_pk_add_f32 v[170:171], v[170:171], v[222:223] op_sel_hi:[1,0]
	v_pk_add_f32 v[172:173], v[172:173], v[222:223] op_sel_hi:[1,0]
	v_pk_add_f32 v[174:175], v[174:175], v[222:223] op_sel_hi:[1,0]
	v_pk_add_f32 v[176:177], v[176:177], v[222:223] op_sel_hi:[1,0]
	v_rcp_f32_e32 v170, v170
	v_rcp_f32_e32 v171, v171
	v_rcp_f32_e32 v172, v172
	v_rcp_f32_e32 v173, v173
	v_rcp_f32_e32 v174, v174
	v_rcp_f32_e32 v175, v175
	v_rcp_f32_e32 v176, v176
	v_rcp_f32_e32 v177, v177
	v_lshlrev_b32_e32 v178, 16, v150
	v_and_b32_e32 v179, 0xffff0000, v150
	v_lshlrev_b32_e32 v180, 16, v146
	v_and_b32_e32 v181, 0xffff0000, v146
	v_pk_fma_f32 v[170:171], v[170:171], v[178:179], v[180:181]
	v_lshlrev_b32_e32 v178, 16, v151
	v_and_b32_e32 v179, 0xffff0000, v151
	v_lshlrev_b32_e32 v180, 16, v147
	v_and_b32_e32 v181, 0xffff0000, v147
	v_pk_fma_f32 v[172:173], v[172:173], v[178:179], v[180:181]
	v_fmac_f32_e32 v248, v170, v170
	v_fmac_f32_e32 v249, v171, v171
	v_cvt_pk_bf16_f32 v166, v170, v171
	v_lshlrev_b32_e32 v178, 16, v152
	v_and_b32_e32 v179, 0xffff0000, v152
	v_lshlrev_b32_e32 v180, 16, v148
	v_and_b32_e32 v181, 0xffff0000, v148
	v_pk_fma_f32 v[174:175], v[174:175], v[178:179], v[180:181]
	v_fmac_f32_e32 v248, v172, v172
	v_fmac_f32_e32 v249, v173, v173
	v_cvt_pk_bf16_f32 v167, v172, v173
	v_lshlrev_b32_e32 v178, 16, v153
	v_and_b32_e32 v179, 0xffff0000, v153
	v_lshlrev_b32_e32 v180, 16, v149
	v_and_b32_e32 v181, 0xffff0000, v149
	v_pk_fma_f32 v[176:177], v[176:177], v[178:179], v[180:181]
	v_fmac_f32_e32 v248, v174, v174
	v_fmac_f32_e32 v249, v175, v175
	v_cvt_pk_bf16_f32 v168, v174, v175
	v_fmac_f32_e32 v248, v176, v176
	v_fmac_f32_e32 v249, v177, v177
	v_cvt_pk_bf16_f32 v169, v176, v177
	s_waitcnt lgkmcnt(0)
	global_store_dwordx4 v[228:229], v[162:165], off offset:256
	v_add_f32_e32 v243, v243, v0
	ds_bpermute_b32 v0, v225, v243
	s_mov_b64 s[20:21], 0x8000
	v_lshl_add_u64 v[230:231], v[186:187], 0, s[20:21]
	ds_bpermute_b32 v244, v223, v166
	ds_bpermute_b32 v245, v223, v167
	ds_bpermute_b32 v246, v223, v168
	ds_bpermute_b32 v247, v223, v169
	v_pk_mul_f32 v[170:171], v[102:103], v[214:215] op_sel:[0,1] op_sel_hi:[1,1]
	v_pk_mul_f32 v[172:173], v[104:105], v[214:215] op_sel:[0,1] op_sel_hi:[1,1]
	v_pk_mul_f32 v[174:175], v[94:95], v[214:215] op_sel:[0,1] op_sel_hi:[1,1]
	v_pk_mul_f32 v[176:177], v[96:97], v[214:215] op_sel:[0,1] op_sel_hi:[1,1]
	v_exp_f32_e32 v170, v170
	v_exp_f32_e32 v171, v171
	v_exp_f32_e32 v172, v172
	v_exp_f32_e32 v173, v173
	v_exp_f32_e32 v174, v174
	v_exp_f32_e32 v175, v175
	v_exp_f32_e32 v176, v176
	v_exp_f32_e32 v177, v177
	v_pk_add_f32 v[170:171], v[170:171], v[222:223] op_sel_hi:[1,0]
	v_pk_add_f32 v[172:173], v[172:173], v[222:223] op_sel_hi:[1,0]
	v_pk_add_f32 v[174:175], v[174:175], v[222:223] op_sel_hi:[1,0]
	v_pk_add_f32 v[176:177], v[176:177], v[222:223] op_sel_hi:[1,0]
	v_rcp_f32_e32 v170, v170
	v_rcp_f32_e32 v171, v171
	v_rcp_f32_e32 v172, v172
	v_rcp_f32_e32 v173, v173
	v_rcp_f32_e32 v174, v174
	v_rcp_f32_e32 v175, v175
	v_rcp_f32_e32 v176, v176
	v_rcp_f32_e32 v177, v177
	v_lshlrev_b32_e32 v178, 16, v158
	v_and_b32_e32 v179, 0xffff0000, v158
	v_lshlrev_b32_e32 v180, 16, v154
	v_and_b32_e32 v181, 0xffff0000, v154
	v_pk_fma_f32 v[170:171], v[170:171], v[178:179], v[180:181]
	v_lshlrev_b32_e32 v178, 16, v159
	v_and_b32_e32 v179, 0xffff0000, v159
	v_lshlrev_b32_e32 v180, 16, v155
	v_and_b32_e32 v181, 0xffff0000, v155
	v_pk_fma_f32 v[172:173], v[172:173], v[178:179], v[180:181]
	v_fmac_f32_e32 v248, v170, v170
	v_fmac_f32_e32 v249, v171, v171
	v_cvt_pk_bf16_f32 v166, v170, v171
	v_lshlrev_b32_e32 v178, 16, v160
	v_and_b32_e32 v179, 0xffff0000, v160
	v_lshlrev_b32_e32 v180, 16, v156
	v_and_b32_e32 v181, 0xffff0000, v156
	v_pk_fma_f32 v[174:175], v[174:175], v[178:179], v[180:181]
	v_fmac_f32_e32 v248, v172, v172
	v_fmac_f32_e32 v249, v173, v173
	v_cvt_pk_bf16_f32 v167, v172, v173
	v_lshlrev_b32_e32 v178, 16, v161
	v_and_b32_e32 v179, 0xffff0000, v161
	v_lshlrev_b32_e32 v180, 16, v157
	v_and_b32_e32 v181, 0xffff0000, v157
	v_pk_fma_f32 v[176:177], v[176:177], v[178:179], v[180:181]
	v_fmac_f32_e32 v248, v174, v174
	v_fmac_f32_e32 v249, v175, v175
	v_cvt_pk_bf16_f32 v168, v174, v175
	v_fmac_f32_e32 v248, v176, v176
	v_fmac_f32_e32 v249, v177, v177
	v_cvt_pk_bf16_f32 v169, v176, v177
	s_waitcnt lgkmcnt(0)
	global_store_dwordx4 v[230:231], v[244:247], off
	v_add_f32_e32 v243, v243, v0
	s_and_saveexec_b64 s[8:9], s[40:41]
	global_store_dword v[192:193], v243, off
	s_or_b64 exec, exec, s[8:9]
	ds_bpermute_b32 v162, v223, v166
	ds_bpermute_b32 v163, v223, v167
	ds_bpermute_b32 v164, v223, v168
	ds_bpermute_b32 v165, v223, v169
	v_add_f32_e32 v248, v248, v249
	ds_bpermute_b32 v0, v224, v248
	s_mov_b64 s[20:21], 0x40000
	v_lshl_add_u64 v[188:189], v[182:183], 0, s[20:21]
	v_lshl_add_u64 v[190:191], v[184:185], 0, s[20:21]
	global_load_dwordx4 v[110:113], v[188:189], off
	global_load_dwordx4 v[106:109], v[190:191], off
	global_load_dwordx4 v[102:105], v[188:189], off offset:256
	global_load_dwordx4 v[94:97], v[190:191], off offset:256
	s_mov_b64 s[20:21], 0x48000
	v_lshl_add_u64 v[188:189], v[182:183], 0, s[20:21]
	v_lshl_add_u64 v[190:191], v[184:185], 0, s[20:21]
	global_load_dwordx4 v[146:149], v[188:189], off
	global_load_dwordx4 v[150:153], v[190:191], off
	global_load_dwordx4 v[154:157], v[188:189], off offset:256
	global_load_dwordx4 v[158:161], v[190:191], off offset:256
	s_waitcnt vmcnt(15)
; __device__ __forceinline__ float bf_lo(unsigned w) { return __uint_as_float(w << 16); }
; __device__ __forceinline__ float bf_hi(unsigned w) { return __uint_as_float(w & 0xffff0000u); }
; __device__ __forceinline__ float sigm(float v) { return __builtin_amdgcn_rcpf(1.0f + __builtin_amdgcn_exp2f(-1.44269504089f * v)); }
; __device__ __forceinline__ u32x4 pack8(const f32x4& v0, const f32x4& v1) { u32x4 w; w.x = cvt_pk_bf16(v0[0], v0[1]); w.y = cvt_pk_bf16(v0[2], v0[3]); w.z = cvt_pk_bf16(v1[0], v1[1]); w.w = cvt_pk_bf16(v1[2], v1[3]); return w; }
; __device__ __forceinline__ float sumsq8(const f32x4& v0, const f32x4& v1) { return (v0[0] * v0[0] + v0[1] * v0[1]) + (v0[2] * v0[2] + v0[3] * v0[3]) + (v1[0] * v1[0] + v1[1] * v1[1]) + (v1[2] * v1[2] + v1[3] * v1[3]); }
; __device__ __forceinline__ void epi_run(const Epi& E, f32x4 (&acc)[2][2][4][2], const Unit& u, int wr, int wc, int fr, int fq) {
;     ...
;                 for (int mm = 0; mm < 2; ++mm) { const int m = 2 * mh + mm, row = row0 + ai * 128 + m * 16; float sq = 0.f;
; #pragma unroll
;                     for (int bj = 0; bj < 2; ++bj) { const u32x4 xx = x[mm][bj], cc = c[mm][bj];
;                         const f32x4 c0 = (f32x4){bf_lo(cc.x), bf_hi(cc.x), bf_lo(cc.y), bf_hi(cc.y)}, c1 = (f32x4){bf_lo(cc.z), bf_hi(cc.z), bf_lo(cc.w), bf_hi(cc.w)};
;                         f32x4 v0 = acc[ai][bj][m][0] * rs[ai][m], v1 = acc[ai][bj][m][1] * rs[ai][m];
; #pragma unroll
;                         for (int e = 0; e < 4; ++e) { v0[e] = sigm(v0[e]) * c0[e]; v1[e] = sigm(v1[e]) * c1[e]; }
;                         const f32x4 x0 = (f32x4){bf_lo(xx.x), bf_hi(xx.x), bf_lo(xx.y), bf_hi(xx.y)} + v0, x1 = (f32x4){bf_lo(xx.z), bf_hi(xx.z), bf_lo(xx.w), bf_hi(xx.w)} + v1;
;                         sq += sumsq8(x0, x1); *(u32x4*)(E.xout16 + (size_t)row * D + col0 + bj * 128) = pack8(x0, x1); }
;                     sq += __shfl_xor(sq, 16); sq += __shfl_xor(sq, 32); if (fq == 0) sslot[row] = sq; }
	v_mov_b32_e32 v243, 0
	v_mov_b32_e32 v249, 0
	v_pk_mul_f32 v[170:171], v[98:99], v[216:217] op_sel_hi:[1,0]
	v_pk_mul_f32 v[172:173], v[100:101], v[216:217] op_sel_hi:[1,0]
	v_pk_mul_f32 v[174:175], v[90:91], v[216:217] op_sel_hi:[1,0]
	v_pk_mul_f32 v[176:177], v[92:93], v[216:217] op_sel_hi:[1,0]
	v_exp_f32_e32 v170, v170
	v_exp_f32_e32 v171, v171
	v_exp_f32_e32 v172, v172
	v_exp_f32_e32 v173, v173
	v_exp_f32_e32 v174, v174
	v_exp_f32_e32 v175, v175
	v_exp_f32_e32 v176, v176
	v_exp_f32_e32 v177, v177
	v_pk_add_f32 v[170:171], v[170:171], v[222:223] op_sel_hi:[1,0]
	v_pk_add_f32 v[172:173], v[172:173], v[222:223] op_sel_hi:[1,0]
	v_pk_add_f32 v[174:175], v[174:175], v[222:223] op_sel_hi:[1,0]
	v_pk_add_f32 v[176:177], v[176:177], v[222:223] op_sel_hi:[1,0]
	v_rcp_f32_e32 v170, v170
	v_rcp_f32_e32 v171, v171
	v_rcp_f32_e32 v172, v172
	v_rcp_f32_e32 v173, v173
	v_rcp_f32_e32 v174, v174
	v_rcp_f32_e32 v175, v175
	v_rcp_f32_e32 v176, v176
	v_rcp_f32_e32 v177, v177
	v_lshlrev_b32_e32 v178, 16, v122
	v_and_b32_e32 v179, 0xffff0000, v122
	v_lshlrev_b32_e32 v180, 16, v126
	v_and_b32_e32 v181, 0xffff0000, v126
	v_pk_fma_f32 v[170:171], v[170:171], v[178:179], v[180:181]
	v_lshlrev_b32_e32 v178, 16, v123
	v_and_b32_e32 v179, 0xffff0000, v123
	v_lshlrev_b32_e32 v180, 16, v127
	v_and_b32_e32 v181, 0xffff0000, v127
	v_pk_fma_f32 v[172:173], v[172:173], v[178:179], v[180:181]
	v_fmac_f32_e32 v243, v170, v170
	v_fmac_f32_e32 v249, v171, v171
	v_cvt_pk_bf16_f32 v166, v170, v171
	v_lshlrev_b32_e32 v178, 16, v124
	v_and_b32_e32 v179, 0xffff0000, v124
	v_lshlrev_b32_e32 v180, 16, v128
	v_and_b32_e32 v181, 0xffff0000, v128
	v_pk_fma_f32 v[174:175], v[174:175], v[178:179], v[180:181]
	v_fmac_f32_e32 v243, v172, v172
	v_fmac_f32_e32 v249, v173, v173
	v_cvt_pk_bf16_f32 v167, v172, v173
	v_lshlrev_b32_e32 v178, 16, v125
	v_and_b32_e32 v179, 0xffff0000, v125
	v_lshlrev_b32_e32 v180, 16, v129
	v_and_b32_e32 v181, 0xffff0000, v129
	v_pk_fma_f32 v[176:177], v[176:177], v[178:179], v[180:181]
	v_fmac_f32_e32 v243, v174, v174
	v_fmac_f32_e32 v249, v175, v175
	v_cvt_pk_bf16_f32 v168, v174, v175
	v_fmac_f32_e32 v243, v176, v176
	v_fmac_f32_e32 v249, v177, v177
	v_cvt_pk_bf16_f32 v169, v176, v177
	s_waitcnt lgkmcnt(0)
	global_store_dwordx4 v[230:231], v[162:165], off offset:256
	v_add_f32_e32 v248, v248, v0
	ds_bpermute_b32 v0, v225, v248
	s_mov_b64 s[20:21], 0x10000
	v_lshl_add_u64 v[228:229], v[186:187], 0, s[20:21]
	ds_bpermute_b32 v244, v223, v166
	ds_bpermute_b32 v245, v223, v167
	ds_bpermute_b32 v246, v223, v168
	ds_bpermute_b32 v247, v223, v169
	v_pk_mul_f32 v[170:171], v[86:87], v[216:217] op_sel_hi:[1,0]
	v_pk_mul_f32 v[172:173], v[88:89], v[216:217] op_sel_hi:[1,0]
	v_pk_mul_f32 v[174:175], v[78:79], v[216:217] op_sel_hi:[1,0]
	v_pk_mul_f32 v[176:177], v[80:81], v[216:217] op_sel_hi:[1,0]
	v_exp_f32_e32 v170, v170
	v_exp_f32_e32 v171, v171
	v_exp_f32_e32 v172, v172
	v_exp_f32_e32 v173, v173
	v_exp_f32_e32 v174, v174
	v_exp_f32_e32 v175, v175
	v_exp_f32_e32 v176, v176
	v_exp_f32_e32 v177, v177
	v_pk_add_f32 v[170:171], v[170:171], v[222:223] op_sel_hi:[1,0]
	v_pk_add_f32 v[172:173], v[172:173], v[222:223] op_sel_hi:[1,0]
	v_pk_add_f32 v[174:175], v[174:175], v[222:223] op_sel_hi:[1,0]
	v_pk_add_f32 v[176:177], v[176:177], v[222:223] op_sel_hi:[1,0]
	v_rcp_f32_e32 v170, v170
	v_rcp_f32_e32 v171, v171
	v_rcp_f32_e32 v172, v172
	v_rcp_f32_e32 v173, v173
	v_rcp_f32_e32 v174, v174
	v_rcp_f32_e32 v175, v175
	v_rcp_f32_e32 v176, v176
	v_rcp_f32_e32 v177, v177
	v_lshlrev_b32_e32 v178, 16, v114
	v_and_b32_e32 v179, 0xffff0000, v114
	v_lshlrev_b32_e32 v180, 16, v118
	v_and_b32_e32 v181, 0xffff0000, v118
	v_pk_fma_f32 v[170:171], v[170:171], v[178:179], v[180:181]
	v_lshlrev_b32_e32 v178, 16, v115
	v_and_b32_e32 v179, 0xffff0000, v115
	v_lshlrev_b32_e32 v180, 16, v119
	v_and_b32_e32 v181, 0xffff0000, v119
	v_pk_fma_f32 v[172:173], v[172:173], v[178:179], v[180:181]
	v_fmac_f32_e32 v243, v170, v170
	v_fmac_f32_e32 v249, v171, v171
	v_cvt_pk_bf16_f32 v166, v170, v171
	v_lshlrev_b32_e32 v178, 16, v116
	v_and_b32_e32 v179, 0xffff0000, v116
	v_lshlrev_b32_e32 v180, 16, v120
	v_and_b32_e32 v181, 0xffff0000, v120
	v_pk_fma_f32 v[174:175], v[174:175], v[178:179], v[180:181]
	v_fmac_f32_e32 v243, v172, v172
	v_fmac_f32_e32 v249, v173, v173
	v_cvt_pk_bf16_f32 v167, v172, v173
	v_lshlrev_b32_e32 v178, 16, v117
	v_and_b32_e32 v179, 0xffff0000, v117
	v_lshlrev_b32_e32 v180, 16, v121
	v_and_b32_e32 v181, 0xffff0000, v121
	v_pk_fma_f32 v[176:177], v[176:177], v[178:179], v[180:181]
	v_fmac_f32_e32 v243, v174, v174
	v_fmac_f32_e32 v249, v175, v175
	v_cvt_pk_bf16_f32 v168, v174, v175
	v_fmac_f32_e32 v243, v176, v176
	v_fmac_f32_e32 v249, v177, v177
	v_cvt_pk_bf16_f32 v169, v176, v177
	s_waitcnt lgkmcnt(0)
	global_store_dwordx4 v[228:229], v[244:247], off
	v_add_f32_e32 v248, v248, v0
	s_and_saveexec_b64 s[8:9], s[40:41]
	global_store_dword v[192:193], v248, off offset:64
	s_or_b64 exec, exec, s[8:9]
	ds_bpermute_b32 v162, v223, v166
	ds_bpermute_b32 v163, v223, v167
	ds_bpermute_b32 v164, v223, v168
	ds_bpermute_b32 v165, v223, v169
	v_add_f32_e32 v243, v243, v249
	ds_bpermute_b32 v0, v224, v243
	s_mov_b64 s[20:21], 0x50000
	v_lshl_add_u64 v[188:189], v[182:183], 0, s[20:21]
	v_lshl_add_u64 v[190:191], v[184:185], 0, s[20:21]
	global_load_dwordx4 v[98:101], v[188:189], off
	global_load_dwordx4 v[90:93], v[190:191], off
	global_load_dwordx4 v[86:89], v[188:189], off offset:256
	global_load_dwordx4 v[78:81], v[190:191], off offset:256
	s_mov_b64 s[20:21], 0x58000
	v_lshl_add_u64 v[188:189], v[182:183], 0, s[20:21]
	v_lshl_add_u64 v[190:191], v[184:185], 0, s[20:21]
	global_load_dwordx4 v[126:129], v[188:189], off
	global_load_dwordx4 v[122:125], v[190:191], off
	global_load_dwordx4 v[118:121], v[188:189], off offset:256
	global_load_dwordx4 v[114:117], v[190:191], off offset:256
	s_waitcnt vmcnt(22)
; __device__ __forceinline__ float bf_lo(unsigned w) { return __uint_as_float(w << 16); }
; __device__ __forceinline__ float bf_hi(unsigned w) { return __uint_as_float(w & 0xffff0000u); }
; __device__ __forceinline__ float sigm(float v) { return __builtin_amdgcn_rcpf(1.0f + __builtin_amdgcn_exp2f(-1.44269504089f * v)); }
; __device__ __forceinline__ u32x4 pack8(const f32x4& v0, const f32x4& v1) { u32x4 w; w.x = cvt_pk_bf16(v0[0], v0[1]); w.y = cvt_pk_bf16(v0[2], v0[3]); w.z = cvt_pk_bf16(v1[0], v1[1]); w.w = cvt_pk_bf16(v1[2], v1[3]); return w; }
; __device__ __forceinline__ float sumsq8(const f32x4& v0, const f32x4& v1) { return (v0[0] * v0[0] + v0[1] * v0[1]) + (v0[2] * v0[2] + v0[3] * v0[3]) + (v1[0] * v1[0] + v1[1] * v1[1]) + (v1[2] * v1[2] + v1[3] * v1[3]); }
; __device__ __forceinline__ void epi_run(const Epi& E, f32x4 (&acc)[2][2][4][2], const Unit& u, int wr, int wc, int fr, int fq) {
;     ...
;                 for (int mm = 0; mm < 2; ++mm) { const int m = 2 * mh + mm, row = row0 + ai * 128 + m * 16; float sq = 0.f;
; #pragma unroll
;                     for (int bj = 0; bj < 2; ++bj) { const u32x4 xx = x[mm][bj], cc = c[mm][bj];
;                         const f32x4 c0 = (f32x4){bf_lo(cc.x), bf_hi(cc.x), bf_lo(cc.y), bf_hi(cc.y)}, c1 = (f32x4){bf_lo(cc.z), bf_hi(cc.z), bf_lo(cc.w), bf_hi(cc.w)};
;                         f32x4 v0 = acc[ai][bj][m][0] * rs[ai][m], v1 = acc[ai][bj][m][1] * rs[ai][m];
; #pragma unroll
;                         for (int e = 0; e < 4; ++e) { v0[e] = sigm(v0[e]) * c0[e]; v1[e] = sigm(v1[e]) * c1[e]; }
;                         const f32x4 x0 = (f32x4){bf_lo(xx.x), bf_hi(xx.x), bf_lo(xx.y), bf_hi(xx.y)} + v0, x1 = (f32x4){bf_lo(xx.z), bf_hi(xx.z), bf_lo(xx.w), bf_hi(xx.w)} + v1;
;                         sq += sumsq8(x0, x1); *(u32x4*)(E.xout16 + (size_t)row * D + col0 + bj * 128) = pack8(x0, x1); }
;                     sq += __shfl_xor(sq, 16); sq += __shfl_xor(sq, 32); if (fq == 0) sslot[row] = sq; }
	v_mov_b32_e32 v248, 0
	v_mov_b32_e32 v249, 0
	v_pk_mul_f32 v[170:171], v[82:83], v[216:217] op_sel:[0,1] op_sel_hi:[1,1]
	v_pk_mul_f32 v[172:173], v[84:85], v[216:217] op_sel:[0,1] op_sel_hi:[1,1]
	v_pk_mul_f32 v[174:175], v[74:75], v[216:217] op_sel:[0,1] op_sel_hi:[1,1]
	v_pk_mul_f32 v[176:177], v[76:77], v[216:217] op_sel:[0,1] op_sel_hi:[1,1]
	v_exp_f32_e32 v170, v170
	v_exp_f32_e32 v171, v171
	v_exp_f32_e32 v172, v172
	v_exp_f32_e32 v173, v173
	v_exp_f32_e32 v174, v174
	v_exp_f32_e32 v175, v175
	v_exp_f32_e32 v176, v176
	v_exp_f32_e32 v177, v177
	v_pk_add_f32 v[170:171], v[170:171], v[222:223] op_sel_hi:[1,0]
	v_pk_add_f32 v[172:173], v[172:173], v[222:223] op_sel_hi:[1,0]
	v_pk_add_f32 v[174:175], v[174:175], v[222:223] op_sel_hi:[1,0]
	v_pk_add_f32 v[176:177], v[176:177], v[222:223] op_sel_hi:[1,0]
	v_rcp_f32_e32 v170, v170
	v_rcp_f32_e32 v171, v171
	v_rcp_f32_e32 v172, v172
	v_rcp_f32_e32 v173, v173
	v_rcp_f32_e32 v174, v174
	v_rcp_f32_e32 v175, v175
	v_rcp_f32_e32 v176, v176
	v_rcp_f32_e32 v177, v177
	v_lshlrev_b32_e32 v178, 16, v134
	v_and_b32_e32 v179, 0xffff0000, v134
	v_lshlrev_b32_e32 v180, 16, v130
	v_and_b32_e32 v181, 0xffff0000, v130
	v_pk_fma_f32 v[170:171], v[170:171], v[178:179], v[180:181]
	v_lshlrev_b32_e32 v178, 16, v135
	v_and_b32_e32 v179, 0xffff0000, v135
	v_lshlrev_b32_e32 v180, 16, v131
	v_and_b32_e32 v181, 0xffff0000, v131
	v_pk_fma_f32 v[172:173], v[172:173], v[178:179], v[180:181]
	v_fmac_f32_e32 v248, v170, v170
	v_fmac_f32_e32 v249, v171, v171
	v_cvt_pk_bf16_f32 v166, v170, v171
	v_lshlrev_b32_e32 v178, 16, v136
	v_and_b32_e32 v179, 0xffff0000, v136
	v_lshlrev_b32_e32 v180, 16, v132
	v_and_b32_e32 v181, 0xffff0000, v132
	v_pk_fma_f32 v[174:175], v[174:175], v[178:179], v[180:181]
	v_fmac_f32_e32 v248, v172, v172
	v_fmac_f32_e32 v249, v173, v173
	v_cvt_pk_bf16_f32 v167, v172, v173
	v_lshlrev_b32_e32 v178, 16, v137
	v_and_b32_e32 v179, 0xffff0000, v137
	v_lshlrev_b32_e32 v180, 16, v133
	v_and_b32_e32 v181, 0xffff0000, v133
	v_pk_fma_f32 v[176:177], v[176:177], v[178:179], v[180:181]
	v_fmac_f32_e32 v248, v174, v174
	v_fmac_f32_e32 v249, v175, v175
	v_cvt_pk_bf16_f32 v168, v174, v175
	v_fmac_f32_e32 v248, v176, v176
	v_fmac_f32_e32 v249, v177, v177
	v_cvt_pk_bf16_f32 v169, v176, v177
	s_waitcnt lgkmcnt(0)
	global_store_dwordx4 v[228:229], v[162:165], off offset:256
	v_add_f32_e32 v243, v243, v0
	ds_bpermute_b32 v0, v225, v243
	s_mov_b64 s[20:21], 0x18000
	v_lshl_add_u64 v[230:231], v[186:187], 0, s[20:21]
	ds_bpermute_b32 v244, v223, v166
	ds_bpermute_b32 v245, v223, v167
	ds_bpermute_b32 v246, v223, v168
	ds_bpermute_b32 v247, v223, v169
	v_pk_mul_f32 v[170:171], v[70:71], v[216:217] op_sel:[0,1] op_sel_hi:[1,1]
	v_pk_mul_f32 v[172:173], v[72:73], v[216:217] op_sel:[0,1] op_sel_hi:[1,1]
	v_pk_mul_f32 v[174:175], v[66:67], v[216:217] op_sel:[0,1] op_sel_hi:[1,1]
	v_pk_mul_f32 v[176:177], v[68:69], v[216:217] op_sel:[0,1] op_sel_hi:[1,1]
	v_exp_f32_e32 v170, v170
	v_exp_f32_e32 v171, v171
	v_exp_f32_e32 v172, v172
	v_exp_f32_e32 v173, v173
	v_exp_f32_e32 v174, v174
	v_exp_f32_e32 v175, v175
	v_exp_f32_e32 v176, v176
	v_exp_f32_e32 v177, v177
	v_pk_add_f32 v[170:171], v[170:171], v[222:223] op_sel_hi:[1,0]
	v_pk_add_f32 v[172:173], v[172:173], v[222:223] op_sel_hi:[1,0]
	v_pk_add_f32 v[174:175], v[174:175], v[222:223] op_sel_hi:[1,0]
	v_pk_add_f32 v[176:177], v[176:177], v[222:223] op_sel_hi:[1,0]
	v_rcp_f32_e32 v170, v170
	v_rcp_f32_e32 v171, v171
	v_rcp_f32_e32 v172, v172
	v_rcp_f32_e32 v173, v173
	v_rcp_f32_e32 v174, v174
	v_rcp_f32_e32 v175, v175
	v_rcp_f32_e32 v176, v176
	v_rcp_f32_e32 v177, v177
	v_lshlrev_b32_e32 v178, 16, v142
	v_and_b32_e32 v179, 0xffff0000, v142
	v_lshlrev_b32_e32 v180, 16, v138
	v_and_b32_e32 v181, 0xffff0000, v138
	v_pk_fma_f32 v[170:171], v[170:171], v[178:179], v[180:181]
	v_lshlrev_b32_e32 v178, 16, v143
	v_and_b32_e32 v179, 0xffff0000, v143
	v_lshlrev_b32_e32 v180, 16, v139
	v_and_b32_e32 v181, 0xffff0000, v139
	v_pk_fma_f32 v[172:173], v[172:173], v[178:179], v[180:181]
	v_fmac_f32_e32 v248, v170, v170
	v_fmac_f32_e32 v249, v171, v171
	v_cvt_pk_bf16_f32 v166, v170, v171
	v_lshlrev_b32_e32 v178, 16, v144
	v_and_b32_e32 v179, 0xffff0000, v144
	v_lshlrev_b32_e32 v180, 16, v140
	v_and_b32_e32 v181, 0xffff0000, v140
	v_pk_fma_f32 v[174:175], v[174:175], v[178:179], v[180:181]
	v_fmac_f32_e32 v248, v172, v172
	v_fmac_f32_e32 v249, v173, v173
	v_cvt_pk_bf16_f32 v167, v172, v173
	v_lshlrev_b32_e32 v178, 16, v145
	v_and_b32_e32 v179, 0xffff0000, v145
	v_lshlrev_b32_e32 v180, 16, v141
	v_and_b32_e32 v181, 0xffff0000, v141
	v_pk_fma_f32 v[176:177], v[176:177], v[178:179], v[180:181]
	v_fmac_f32_e32 v248, v174, v174
	v_fmac_f32_e32 v249, v175, v175
	v_cvt_pk_bf16_f32 v168, v174, v175
	v_fmac_f32_e32 v248, v176, v176
	v_fmac_f32_e32 v249, v177, v177
	v_cvt_pk_bf16_f32 v169, v176, v177
	s_waitcnt lgkmcnt(0)
	global_store_dwordx4 v[230:231], v[244:247], off
	v_add_f32_e32 v243, v243, v0
	s_and_saveexec_b64 s[8:9], s[40:41]
	global_store_dword v[192:193], v243, off offset:128
	s_or_b64 exec, exec, s[8:9]
	ds_bpermute_b32 v162, v223, v166
	ds_bpermute_b32 v163, v223, v167
	ds_bpermute_b32 v164, v223, v168
	ds_bpermute_b32 v165, v223, v169
	v_add_f32_e32 v248, v248, v249
	ds_bpermute_b32 v0, v224, v248
	s_waitcnt vmcnt(18)
; __device__ __forceinline__ float bf_lo(unsigned w) { return __uint_as_float(w << 16); }
; __device__ __forceinline__ float bf_hi(unsigned w) { return __uint_as_float(w & 0xffff0000u); }
; __device__ __forceinline__ float sigm(float v) { return __builtin_amdgcn_rcpf(1.0f + __builtin_amdgcn_exp2f(-1.44269504089f * v)); }
; __device__ __forceinline__ u32x4 pack8(const f32x4& v0, const f32x4& v1) { u32x4 w; w.x = cvt_pk_bf16(v0[0], v0[1]); w.y = cvt_pk_bf16(v0[2], v0[3]); w.z = cvt_pk_bf16(v1[0], v1[1]); w.w = cvt_pk_bf16(v1[2], v1[3]); return w; }
; __device__ __forceinline__ float sumsq8(const f32x4& v0, const f32x4& v1) { return (v0[0] * v0[0] + v0[1] * v0[1]) + (v0[2] * v0[2] + v0[3] * v0[3]) + (v1[0] * v1[0] + v1[1] * v1[1]) + (v1[2] * v1[2] + v1[3] * v1[3]); }
; __device__ __forceinline__ void epi_run(const Epi& E, f32x4 (&acc)[2][2][4][2], const Unit& u, int wr, int wc, int fr, int fq) {
;     ...
;                 for (int mm = 0; mm < 2; ++mm) { const int m = 2 * mh + mm, row = row0 + ai * 128 + m * 16; float sq = 0.f;
; #pragma unroll
;                     for (int bj = 0; bj < 2; ++bj) { const u32x4 xx = x[mm][bj], cc = c[mm][bj];
;                         const f32x4 c0 = (f32x4){bf_lo(cc.x), bf_hi(cc.x), bf_lo(cc.y), bf_hi(cc.y)}, c1 = (f32x4){bf_lo(cc.z), bf_hi(cc.z), bf_lo(cc.w), bf_hi(cc.w)};
;                         f32x4 v0 = acc[ai][bj][m][0] * rs[ai][m], v1 = acc[ai][bj][m][1] * rs[ai][m];
; #pragma unroll
;                         for (int e = 0; e < 4; ++e) { v0[e] = sigm(v0[e]) * c0[e]; v1[e] = sigm(v1[e]) * c1[e]; }
;                         const f32x4 x0 = (f32x4){bf_lo(xx.x), bf_hi(xx.x), bf_lo(xx.y), bf_hi(xx.y)} + v0, x1 = (f32x4){bf_lo(xx.z), bf_hi(xx.z), bf_lo(xx.w), bf_hi(xx.w)} + v1;
;                         sq += sumsq8(x0, x1); *(u32x4*)(E.xout16 + (size_t)row * D + col0 + bj * 128) = pack8(x0, x1); }
;                     sq += __shfl_xor(sq, 16); sq += __shfl_xor(sq, 32); if (fq == 0) sslot[row] = sq; }
	v_mov_b32_e32 v243, 0
	v_mov_b32_e32 v249, 0
	v_pk_mul_f32 v[170:171], v[62:63], v[218:219] op_sel_hi:[1,0]
	v_pk_mul_f32 v[172:173], v[64:65], v[218:219] op_sel_hi:[1,0]
	v_pk_mul_f32 v[174:175], v[58:59], v[218:219] op_sel_hi:[1,0]
	v_pk_mul_f32 v[176:177], v[60:61], v[218:219] op_sel_hi:[1,0]
	v_exp_f32_e32 v170, v170
	v_exp_f32_e32 v171, v171
	v_exp_f32_e32 v172, v172
	v_exp_f32_e32 v173, v173
	v_exp_f32_e32 v174, v174
	v_exp_f32_e32 v175, v175
	v_exp_f32_e32 v176, v176
	v_exp_f32_e32 v177, v177
	v_pk_add_f32 v[170:171], v[170:171], v[222:223] op_sel_hi:[1,0]
	v_pk_add_f32 v[172:173], v[172:173], v[222:223] op_sel_hi:[1,0]
	v_pk_add_f32 v[174:175], v[174:175], v[222:223] op_sel_hi:[1,0]
	v_pk_add_f32 v[176:177], v[176:177], v[222:223] op_sel_hi:[1,0]
	v_rcp_f32_e32 v170, v170
	v_rcp_f32_e32 v171, v171
	v_rcp_f32_e32 v172, v172
	v_rcp_f32_e32 v173, v173
	v_rcp_f32_e32 v174, v174
	v_rcp_f32_e32 v175, v175
	v_rcp_f32_e32 v176, v176
	v_rcp_f32_e32 v177, v177
	v_lshlrev_b32_e32 v178, 16, v106
	v_and_b32_e32 v179, 0xffff0000, v106
	v_lshlrev_b32_e32 v180, 16, v110
	v_and_b32_e32 v181, 0xffff0000, v110
	v_pk_fma_f32 v[170:171], v[170:171], v[178:179], v[180:181]
	v_lshlrev_b32_e32 v178, 16, v107
	v_and_b32_e32 v179, 0xffff0000, v107
	v_lshlrev_b32_e32 v180, 16, v111
	v_and_b32_e32 v181, 0xffff0000, v111
	v_pk_fma_f32 v[172:173], v[172:173], v[178:179], v[180:181]
	v_fmac_f32_e32 v243, v170, v170
	v_fmac_f32_e32 v249, v171, v171
	v_cvt_pk_bf16_f32 v166, v170, v171
	v_lshlrev_b32_e32 v178, 16, v108
	v_and_b32_e32 v179, 0xffff0000, v108
	v_lshlrev_b32_e32 v180, 16, v112
	v_and_b32_e32 v181, 0xffff0000, v112
	v_pk_fma_f32 v[174:175], v[174:175], v[178:179], v[180:181]
	v_fmac_f32_e32 v243, v172, v172
	v_fmac_f32_e32 v249, v173, v173
	v_cvt_pk_bf16_f32 v167, v172, v173
	v_lshlrev_b32_e32 v178, 16, v109
	v_and_b32_e32 v179, 0xffff0000, v109
	v_lshlrev_b32_e32 v180, 16, v113
	v_and_b32_e32 v181, 0xffff0000, v113
	v_pk_fma_f32 v[176:177], v[176:177], v[178:179], v[180:181]
	v_fmac_f32_e32 v243, v174, v174
	v_fmac_f32_e32 v249, v175, v175
	v_cvt_pk_bf16_f32 v168, v174, v175
	v_fmac_f32_e32 v243, v176, v176
	v_fmac_f32_e32 v249, v177, v177
	v_cvt_pk_bf16_f32 v169, v176, v177
	s_waitcnt lgkmcnt(0)
	global_store_dwordx4 v[230:231], v[162:165], off offset:256
	v_add_f32_e32 v248, v248, v0
	ds_bpermute_b32 v0, v225, v248
	s_mov_b64 s[20:21], 0x40000
	v_lshl_add_u64 v[228:229], v[186:187], 0, s[20:21]
	ds_bpermute_b32 v244, v223, v166
	ds_bpermute_b32 v245, v223, v167
	ds_bpermute_b32 v246, v223, v168
	ds_bpermute_b32 v247, v223, v169
	v_pk_mul_f32 v[170:171], v[54:55], v[218:219] op_sel_hi:[1,0]
	v_pk_mul_f32 v[172:173], v[56:57], v[218:219] op_sel_hi:[1,0]
	v_pk_mul_f32 v[174:175], v[50:51], v[218:219] op_sel_hi:[1,0]
	v_pk_mul_f32 v[176:177], v[52:53], v[218:219] op_sel_hi:[1,0]
	v_exp_f32_e32 v170, v170
	v_exp_f32_e32 v171, v171
	v_exp_f32_e32 v172, v172
	v_exp_f32_e32 v173, v173
	v_exp_f32_e32 v174, v174
	v_exp_f32_e32 v175, v175
	v_exp_f32_e32 v176, v176
	v_exp_f32_e32 v177, v177
	v_pk_add_f32 v[170:171], v[170:171], v[222:223] op_sel_hi:[1,0]
	v_pk_add_f32 v[172:173], v[172:173], v[222:223] op_sel_hi:[1,0]
	v_pk_add_f32 v[174:175], v[174:175], v[222:223] op_sel_hi:[1,0]
	v_pk_add_f32 v[176:177], v[176:177], v[222:223] op_sel_hi:[1,0]
	v_rcp_f32_e32 v170, v170
	v_rcp_f32_e32 v171, v171
	v_rcp_f32_e32 v172, v172
	v_rcp_f32_e32 v173, v173
	v_rcp_f32_e32 v174, v174
	v_rcp_f32_e32 v175, v175
	v_rcp_f32_e32 v176, v176
	v_rcp_f32_e32 v177, v177
	v_lshlrev_b32_e32 v178, 16, v94
	v_and_b32_e32 v179, 0xffff0000, v94
	v_lshlrev_b32_e32 v180, 16, v102
	v_and_b32_e32 v181, 0xffff0000, v102
	v_pk_fma_f32 v[170:171], v[170:171], v[178:179], v[180:181]
	v_lshlrev_b32_e32 v178, 16, v95
	v_and_b32_e32 v179, 0xffff0000, v95
	v_lshlrev_b32_e32 v180, 16, v103
	v_and_b32_e32 v181, 0xffff0000, v103
	v_pk_fma_f32 v[172:173], v[172:173], v[178:179], v[180:181]
	v_fmac_f32_e32 v243, v170, v170
	v_fmac_f32_e32 v249, v171, v171
	v_cvt_pk_bf16_f32 v166, v170, v171
	v_lshlrev_b32_e32 v178, 16, v96
	v_and_b32_e32 v179, 0xffff0000, v96
	v_lshlrev_b32_e32 v180, 16, v104
	v_and_b32_e32 v181, 0xffff0000, v104
	v_pk_fma_f32 v[174:175], v[174:175], v[178:179], v[180:181]
	v_fmac_f32_e32 v243, v172, v172
	v_fmac_f32_e32 v249, v173, v173
	v_cvt_pk_bf16_f32 v167, v172, v173
	v_lshlrev_b32_e32 v178, 16, v97
	v_and_b32_e32 v179, 0xffff0000, v97
	v_lshlrev_b32_e32 v180, 16, v105
	v_and_b32_e32 v181, 0xffff0000, v105
	v_pk_fma_f32 v[176:177], v[176:177], v[178:179], v[180:181]
	v_fmac_f32_e32 v243, v174, v174
	v_fmac_f32_e32 v249, v175, v175
	v_cvt_pk_bf16_f32 v168, v174, v175
	v_fmac_f32_e32 v243, v176, v176
	v_fmac_f32_e32 v249, v177, v177
	v_cvt_pk_bf16_f32 v169, v176, v177
	s_waitcnt lgkmcnt(0)
	global_store_dwordx4 v[228:229], v[244:247], off
	v_add_f32_e32 v248, v248, v0
	s_and_saveexec_b64 s[8:9], s[40:41]
	global_store_dword v[192:193], v248, off offset:192
	s_or_b64 exec, exec, s[8:9]
	ds_bpermute_b32 v162, v223, v166
	ds_bpermute_b32 v163, v223, v167
	ds_bpermute_b32 v164, v223, v168
	ds_bpermute_b32 v165, v223, v169
	v_add_f32_e32 v243, v243, v249
	ds_bpermute_b32 v0, v224, v243
	s_waitcnt vmcnt(17)
; __device__ __forceinline__ float bf_lo(unsigned w) { return __uint_as_float(w << 16); }
; __device__ __forceinline__ float bf_hi(unsigned w) { return __uint_as_float(w & 0xffff0000u); }
; __device__ __forceinline__ float sigm(float v) { return __builtin_amdgcn_rcpf(1.0f + __builtin_amdgcn_exp2f(-1.44269504089f * v)); }
; __device__ __forceinline__ u32x4 pack8(const f32x4& v0, const f32x4& v1) { u32x4 w; w.x = cvt_pk_bf16(v0[0], v0[1]); w.y = cvt_pk_bf16(v0[2], v0[3]); w.z = cvt_pk_bf16(v1[0], v1[1]); w.w = cvt_pk_bf16(v1[2], v1[3]); return w; }
; __device__ __forceinline__ float sumsq8(const f32x4& v0, const f32x4& v1) { return (v0[0] * v0[0] + v0[1] * v0[1]) + (v0[2] * v0[2] + v0[3] * v0[3]) + (v1[0] * v1[0] + v1[1] * v1[1]) + (v1[2] * v1[2] + v1[3] * v1[3]); }
; __device__ __forceinline__ void epi_run(const Epi& E, f32x4 (&acc)[2][2][4][2], const Unit& u, int wr, int wc, int fr, int fq) {
;     ...
;                 for (int mm = 0; mm < 2; ++mm) { const int m = 2 * mh + mm, row = row0 + ai * 128 + m * 16; float sq = 0.f;
; #pragma unroll
;                     for (int bj = 0; bj < 2; ++bj) { const u32x4 xx = x[mm][bj], cc = c[mm][bj];
;                         const f32x4 c0 = (f32x4){bf_lo(cc.x), bf_hi(cc.x), bf_lo(cc.y), bf_hi(cc.y)}, c1 = (f32x4){bf_lo(cc.z), bf_hi(cc.z), bf_lo(cc.w), bf_hi(cc.w)};
;                         f32x4 v0 = acc[ai][bj][m][0] * rs[ai][m], v1 = acc[ai][bj][m][1] * rs[ai][m];
; #pragma unroll
;                         for (int e = 0; e < 4; ++e) { v0[e] = sigm(v0[e]) * c0[e]; v1[e] = sigm(v1[e]) * c1[e]; }
;                         const f32x4 x0 = (f32x4){bf_lo(xx.x), bf_hi(xx.x), bf_lo(xx.y), bf_hi(xx.y)} + v0, x1 = (f32x4){bf_lo(xx.z), bf_hi(xx.z), bf_lo(xx.w), bf_hi(xx.w)} + v1;
;                         sq += sumsq8(x0, x1); *(u32x4*)(E.xout16 + (size_t)row * D + col0 + bj * 128) = pack8(x0, x1); }
;                     sq += __shfl_xor(sq, 16); sq += __shfl_xor(sq, 32); if (fq == 0) sslot[row] = sq; }
	v_mov_b32_e32 v248, 0
	v_mov_b32_e32 v249, 0
	v_pk_mul_f32 v[170:171], v[46:47], v[218:219] op_sel:[0,1] op_sel_hi:[1,1]
	v_pk_mul_f32 v[172:173], v[48:49], v[218:219] op_sel:[0,1] op_sel_hi:[1,1]
	v_pk_mul_f32 v[174:175], v[42:43], v[218:219] op_sel:[0,1] op_sel_hi:[1,1]
	v_pk_mul_f32 v[176:177], v[44:45], v[218:219] op_sel:[0,1] op_sel_hi:[1,1]
	v_exp_f32_e32 v170, v170
	v_exp_f32_e32 v171, v171
	v_exp_f32_e32 v172, v172
	v_exp_f32_e32 v173, v173
	v_exp_f32_e32 v174, v174
	v_exp_f32_e32 v175, v175
	v_exp_f32_e32 v176, v176
	v_exp_f32_e32 v177, v177
	v_pk_add_f32 v[170:171], v[170:171], v[222:223] op_sel_hi:[1,0]
	v_pk_add_f32 v[172:173], v[172:173], v[222:223] op_sel_hi:[1,0]
	v_pk_add_f32 v[174:175], v[174:175], v[222:223] op_sel_hi:[1,0]
	v_pk_add_f32 v[176:177], v[176:177], v[222:223] op_sel_hi:[1,0]
	v_rcp_f32_e32 v170, v170
	v_rcp_f32_e32 v171, v171
	v_rcp_f32_e32 v172, v172
	v_rcp_f32_e32 v173, v173
	v_rcp_f32_e32 v174, v174
	v_rcp_f32_e32 v175, v175
	v_rcp_f32_e32 v176, v176
	v_rcp_f32_e32 v177, v177
	v_lshlrev_b32_e32 v178, 16, v150
	v_and_b32_e32 v179, 0xffff0000, v150
	v_lshlrev_b32_e32 v180, 16, v146
	v_and_b32_e32 v181, 0xffff0000, v146
	v_pk_fma_f32 v[170:171], v[170:171], v[178:179], v[180:181]
	v_lshlrev_b32_e32 v178, 16, v151
	v_and_b32_e32 v179, 0xffff0000, v151
	v_lshlrev_b32_e32 v180, 16, v147
	v_and_b32_e32 v181, 0xffff0000, v147
	v_pk_fma_f32 v[172:173], v[172:173], v[178:179], v[180:181]
	v_fmac_f32_e32 v248, v170, v170
	v_fmac_f32_e32 v249, v171, v171
	v_cvt_pk_bf16_f32 v166, v170, v171
	v_lshlrev_b32_e32 v178, 16, v152
	v_and_b32_e32 v179, 0xffff0000, v152
	v_lshlrev_b32_e32 v180, 16, v148
	v_and_b32_e32 v181, 0xffff0000, v148
	v_pk_fma_f32 v[174:175], v[174:175], v[178:179], v[180:181]
	v_fmac_f32_e32 v248, v172, v172
	v_fmac_f32_e32 v249, v173, v173
	v_cvt_pk_bf16_f32 v167, v172, v173
	v_lshlrev_b32_e32 v178, 16, v153
	v_and_b32_e32 v179, 0xffff0000, v153
	v_lshlrev_b32_e32 v180, 16, v149
	v_and_b32_e32 v181, 0xffff0000, v149
	v_pk_fma_f32 v[176:177], v[176:177], v[178:179], v[180:181]
	v_fmac_f32_e32 v248, v174, v174
	v_fmac_f32_e32 v249, v175, v175
	v_cvt_pk_bf16_f32 v168, v174, v175
	v_fmac_f32_e32 v248, v176, v176
	v_fmac_f32_e32 v249, v177, v177
	v_cvt_pk_bf16_f32 v169, v176, v177
	s_waitcnt lgkmcnt(0)
	global_store_dwordx4 v[228:229], v[162:165], off offset:256
	v_add_f32_e32 v243, v243, v0
	ds_bpermute_b32 v0, v225, v243
	s_mov_b64 s[20:21], 0x48000
	v_lshl_add_u64 v[230:231], v[186:187], 0, s[20:21]
	ds_bpermute_b32 v244, v223, v166
	ds_bpermute_b32 v245, v223, v167
	ds_bpermute_b32 v246, v223, v168
	ds_bpermute_b32 v247, v223, v169
	v_pk_mul_f32 v[170:171], v[38:39], v[218:219] op_sel:[0,1] op_sel_hi:[1,1]
	v_pk_mul_f32 v[172:173], v[40:41], v[218:219] op_sel:[0,1] op_sel_hi:[1,1]
	v_pk_mul_f32 v[174:175], v[34:35], v[218:219] op_sel:[0,1] op_sel_hi:[1,1]
	v_pk_mul_f32 v[176:177], v[36:37], v[218:219] op_sel:[0,1] op_sel_hi:[1,1]
	v_exp_f32_e32 v170, v170
	v_exp_f32_e32 v171, v171
	v_exp_f32_e32 v172, v172
	v_exp_f32_e32 v173, v173
	v_exp_f32_e32 v174, v174
	v_exp_f32_e32 v175, v175
	v_exp_f32_e32 v176, v176
	v_exp_f32_e32 v177, v177
	v_pk_add_f32 v[170:171], v[170:171], v[222:223] op_sel_hi:[1,0]
	v_pk_add_f32 v[172:173], v[172:173], v[222:223] op_sel_hi:[1,0]
	v_pk_add_f32 v[174:175], v[174:175], v[222:223] op_sel_hi:[1,0]
	v_pk_add_f32 v[176:177], v[176:177], v[222:223] op_sel_hi:[1,0]
	v_rcp_f32_e32 v170, v170
	v_rcp_f32_e32 v171, v171
	v_rcp_f32_e32 v172, v172
	v_rcp_f32_e32 v173, v173
	v_rcp_f32_e32 v174, v174
	v_rcp_f32_e32 v175, v175
	v_rcp_f32_e32 v176, v176
	v_rcp_f32_e32 v177, v177
	v_lshlrev_b32_e32 v178, 16, v158
	v_and_b32_e32 v179, 0xffff0000, v158
	v_lshlrev_b32_e32 v180, 16, v154
	v_and_b32_e32 v181, 0xffff0000, v154
	v_pk_fma_f32 v[170:171], v[170:171], v[178:179], v[180:181]
	v_lshlrev_b32_e32 v178, 16, v159
	v_and_b32_e32 v179, 0xffff0000, v159
	v_lshlrev_b32_e32 v180, 16, v155
	v_and_b32_e32 v181, 0xffff0000, v155
	v_pk_fma_f32 v[172:173], v[172:173], v[178:179], v[180:181]
	v_fmac_f32_e32 v248, v170, v170
	v_fmac_f32_e32 v249, v171, v171
	v_cvt_pk_bf16_f32 v166, v170, v171
	v_lshlrev_b32_e32 v178, 16, v160
	v_and_b32_e32 v179, 0xffff0000, v160
	v_lshlrev_b32_e32 v180, 16, v156
	v_and_b32_e32 v181, 0xffff0000, v156
	v_pk_fma_f32 v[174:175], v[174:175], v[178:179], v[180:181]
	v_fmac_f32_e32 v248, v172, v172
	v_fmac_f32_e32 v249, v173, v173
	v_cvt_pk_bf16_f32 v167, v172, v173
	v_lshlrev_b32_e32 v178, 16, v161
	v_and_b32_e32 v179, 0xffff0000, v161
	v_lshlrev_b32_e32 v180, 16, v157
	v_and_b32_e32 v181, 0xffff0000, v157
	v_pk_fma_f32 v[176:177], v[176:177], v[178:179], v[180:181]
	v_fmac_f32_e32 v248, v174, v174
	v_fmac_f32_e32 v249, v175, v175
	v_cvt_pk_bf16_f32 v168, v174, v175
	v_fmac_f32_e32 v248, v176, v176
	v_fmac_f32_e32 v249, v177, v177
	v_cvt_pk_bf16_f32 v169, v176, v177
	s_waitcnt lgkmcnt(0)
	global_store_dwordx4 v[230:231], v[244:247], off
	v_add_f32_e32 v243, v243, v0
	s_and_saveexec_b64 s[8:9], s[40:41]
	global_store_dword v[192:193], v243, off offset:512
	s_or_b64 exec, exec, s[8:9]
	ds_bpermute_b32 v162, v223, v166
	ds_bpermute_b32 v163, v223, v167
	ds_bpermute_b32 v164, v223, v168
	ds_bpermute_b32 v165, v223, v169
	v_add_f32_e32 v248, v248, v249
	ds_bpermute_b32 v0, v224, v248
	s_waitcnt vmcnt(13)
; __device__ __forceinline__ float bf_lo(unsigned w) { return __uint_as_float(w << 16); }
; __device__ __forceinline__ float bf_hi(unsigned w) { return __uint_as_float(w & 0xffff0000u); }
; __device__ __forceinline__ float sigm(float v) { return __builtin_amdgcn_rcpf(1.0f + __builtin_amdgcn_exp2f(-1.44269504089f * v)); }
; __device__ __forceinline__ u32x4 pack8(const f32x4& v0, const f32x4& v1) { u32x4 w; w.x = cvt_pk_bf16(v0[0], v0[1]); w.y = cvt_pk_bf16(v0[2], v0[3]); w.z = cvt_pk_bf16(v1[0], v1[1]); w.w = cvt_pk_bf16(v1[2], v1[3]); return w; }
; __device__ __forceinline__ float sumsq8(const f32x4& v0, const f32x4& v1) { return (v0[0] * v0[0] + v0[1] * v0[1]) + (v0[2] * v0[2] + v0[3] * v0[3]) + (v1[0] * v1[0] + v1[1] * v1[1]) + (v1[2] * v1[2] + v1[3] * v1[3]); }
; __device__ __forceinline__ void epi_run(const Epi& E, f32x4 (&acc)[2][2][4][2], const Unit& u, int wr, int wc, int fr, int fq) {
;     ...
;                 for (int mm = 0; mm < 2; ++mm) { const int m = 2 * mh + mm, row = row0 + ai * 128 + m * 16; float sq = 0.f;
; #pragma unroll
;                     for (int bj = 0; bj < 2; ++bj) { const u32x4 xx = x[mm][bj], cc = c[mm][bj];
;                         const f32x4 c0 = (f32x4){bf_lo(cc.x), bf_hi(cc.x), bf_lo(cc.y), bf_hi(cc.y)}, c1 = (f32x4){bf_lo(cc.z), bf_hi(cc.z), bf_lo(cc.w), bf_hi(cc.w)};
;                         f32x4 v0 = acc[ai][bj][m][0] * rs[ai][m], v1 = acc[ai][bj][m][1] * rs[ai][m];
; #pragma unroll
;                         for (int e = 0; e < 4; ++e) { v0[e] = sigm(v0[e]) * c0[e]; v1[e] = sigm(v1[e]) * c1[e]; }
;                         const f32x4 x0 = (f32x4){bf_lo(xx.x), bf_hi(xx.x), bf_lo(xx.y), bf_hi(xx.y)} + v0, x1 = (f32x4){bf_lo(xx.z), bf_hi(xx.z), bf_lo(xx.w), bf_hi(xx.w)} + v1;
;                         sq += sumsq8(x0, x1); *(u32x4*)(E.xout16 + (size_t)row * D + col0 + bj * 128) = pack8(x0, x1); }
;                     sq += __shfl_xor(sq, 16); sq += __shfl_xor(sq, 32); if (fq == 0) sslot[row] = sq; }
	v_mov_b32_e32 v243, 0
	v_mov_b32_e32 v249, 0
	v_pk_mul_f32 v[170:171], v[30:31], v[220:221] op_sel_hi:[1,0]
	v_pk_mul_f32 v[172:173], v[32:33], v[220:221] op_sel_hi:[1,0]
	v_pk_mul_f32 v[174:175], v[26:27], v[220:221] op_sel_hi:[1,0]
	v_pk_mul_f32 v[176:177], v[28:29], v[220:221] op_sel_hi:[1,0]
	v_exp_f32_e32 v170, v170
	v_exp_f32_e32 v171, v171
	v_exp_f32_e32 v172, v172
	v_exp_f32_e32 v173, v173
	v_exp_f32_e32 v174, v174
	v_exp_f32_e32 v175, v175
	v_exp_f32_e32 v176, v176
	v_exp_f32_e32 v177, v177
	v_pk_add_f32 v[170:171], v[170:171], v[222:223] op_sel_hi:[1,0]
	v_pk_add_f32 v[172:173], v[172:173], v[222:223] op_sel_hi:[1,0]
	v_pk_add_f32 v[174:175], v[174:175], v[222:223] op_sel_hi:[1,0]
	v_pk_add_f32 v[176:177], v[176:177], v[222:223] op_sel_hi:[1,0]
	v_rcp_f32_e32 v170, v170
	v_rcp_f32_e32 v171, v171
	v_rcp_f32_e32 v172, v172
	v_rcp_f32_e32 v173, v173
	v_rcp_f32_e32 v174, v174
	v_rcp_f32_e32 v175, v175
	v_rcp_f32_e32 v176, v176
	v_rcp_f32_e32 v177, v177
	v_lshlrev_b32_e32 v178, 16, v90
	v_and_b32_e32 v179, 0xffff0000, v90
	v_lshlrev_b32_e32 v180, 16, v98
	v_and_b32_e32 v181, 0xffff0000, v98
	v_pk_fma_f32 v[170:171], v[170:171], v[178:179], v[180:181]
	v_lshlrev_b32_e32 v178, 16, v91
	v_and_b32_e32 v179, 0xffff0000, v91
	v_lshlrev_b32_e32 v180, 16, v99
	v_and_b32_e32 v181, 0xffff0000, v99
	v_pk_fma_f32 v[172:173], v[172:173], v[178:179], v[180:181]
	v_fmac_f32_e32 v243, v170, v170
	v_fmac_f32_e32 v249, v171, v171
	v_cvt_pk_bf16_f32 v166, v170, v171
	v_lshlrev_b32_e32 v178, 16, v92
	v_and_b32_e32 v179, 0xffff0000, v92
	v_lshlrev_b32_e32 v180, 16, v100
	v_and_b32_e32 v181, 0xffff0000, v100
	v_pk_fma_f32 v[174:175], v[174:175], v[178:179], v[180:181]
	v_fmac_f32_e32 v243, v172, v172
	v_fmac_f32_e32 v249, v173, v173
	v_cvt_pk_bf16_f32 v167, v172, v173
	v_lshlrev_b32_e32 v178, 16, v93
	v_and_b32_e32 v179, 0xffff0000, v93
	v_lshlrev_b32_e32 v180, 16, v101
	v_and_b32_e32 v181, 0xffff0000, v101
	v_pk_fma_f32 v[176:177], v[176:177], v[178:179], v[180:181]
	v_fmac_f32_e32 v243, v174, v174
	v_fmac_f32_e32 v249, v175, v175
	v_cvt_pk_bf16_f32 v168, v174, v175
	v_fmac_f32_e32 v243, v176, v176
	v_fmac_f32_e32 v249, v177, v177
	v_cvt_pk_bf16_f32 v169, v176, v177
	s_waitcnt lgkmcnt(0)
	global_store_dwordx4 v[230:231], v[162:165], off offset:256
	v_add_f32_e32 v248, v248, v0
	ds_bpermute_b32 v0, v225, v248
	s_mov_b64 s[20:21], 0x50000
	v_lshl_add_u64 v[228:229], v[186:187], 0, s[20:21]
	ds_bpermute_b32 v244, v223, v166
	ds_bpermute_b32 v245, v223, v167
	ds_bpermute_b32 v246, v223, v168
	ds_bpermute_b32 v247, v223, v169
	v_pk_mul_f32 v[170:171], v[22:23], v[220:221] op_sel_hi:[1,0]
	v_pk_mul_f32 v[172:173], v[24:25], v[220:221] op_sel_hi:[1,0]
	v_pk_mul_f32 v[174:175], v[18:19], v[220:221] op_sel_hi:[1,0]
	v_pk_mul_f32 v[176:177], v[20:21], v[220:221] op_sel_hi:[1,0]
	v_exp_f32_e32 v170, v170
	v_exp_f32_e32 v171, v171
	v_exp_f32_e32 v172, v172
	v_exp_f32_e32 v173, v173
	v_exp_f32_e32 v174, v174
	v_exp_f32_e32 v175, v175
	v_exp_f32_e32 v176, v176
	v_exp_f32_e32 v177, v177
	v_pk_add_f32 v[170:171], v[170:171], v[222:223] op_sel_hi:[1,0]
	v_pk_add_f32 v[172:173], v[172:173], v[222:223] op_sel_hi:[1,0]
	v_pk_add_f32 v[174:175], v[174:175], v[222:223] op_sel_hi:[1,0]
	v_pk_add_f32 v[176:177], v[176:177], v[222:223] op_sel_hi:[1,0]
	v_rcp_f32_e32 v170, v170
	v_rcp_f32_e32 v171, v171
	v_rcp_f32_e32 v172, v172
	v_rcp_f32_e32 v173, v173
	v_rcp_f32_e32 v174, v174
	v_rcp_f32_e32 v175, v175
	v_rcp_f32_e32 v176, v176
	v_rcp_f32_e32 v177, v177
	v_lshlrev_b32_e32 v178, 16, v78
	v_and_b32_e32 v179, 0xffff0000, v78
	v_lshlrev_b32_e32 v180, 16, v86
	v_and_b32_e32 v181, 0xffff0000, v86
	v_pk_fma_f32 v[170:171], v[170:171], v[178:179], v[180:181]
	v_lshlrev_b32_e32 v178, 16, v79
	v_and_b32_e32 v179, 0xffff0000, v79
	v_lshlrev_b32_e32 v180, 16, v87
	v_and_b32_e32 v181, 0xffff0000, v87
	v_pk_fma_f32 v[172:173], v[172:173], v[178:179], v[180:181]
	v_fmac_f32_e32 v243, v170, v170
	v_fmac_f32_e32 v249, v171, v171
	v_cvt_pk_bf16_f32 v166, v170, v171
	v_lshlrev_b32_e32 v178, 16, v80
	v_and_b32_e32 v179, 0xffff0000, v80
	v_lshlrev_b32_e32 v180, 16, v88
	v_and_b32_e32 v181, 0xffff0000, v88
	v_pk_fma_f32 v[174:175], v[174:175], v[178:179], v[180:181]
	v_fmac_f32_e32 v243, v172, v172
	v_fmac_f32_e32 v249, v173, v173
	v_cvt_pk_bf16_f32 v167, v172, v173
	v_lshlrev_b32_e32 v178, 16, v81
	v_and_b32_e32 v179, 0xffff0000, v81
	v_lshlrev_b32_e32 v180, 16, v89
	v_and_b32_e32 v181, 0xffff0000, v89
	v_pk_fma_f32 v[176:177], v[176:177], v[178:179], v[180:181]
	v_fmac_f32_e32 v243, v174, v174
	v_fmac_f32_e32 v249, v175, v175
	v_cvt_pk_bf16_f32 v168, v174, v175
	v_fmac_f32_e32 v243, v176, v176
	v_fmac_f32_e32 v249, v177, v177
	v_cvt_pk_bf16_f32 v169, v176, v177
	s_waitcnt lgkmcnt(0)
	global_store_dwordx4 v[228:229], v[244:247], off
	v_add_f32_e32 v248, v248, v0
	s_and_saveexec_b64 s[8:9], s[40:41]
	global_store_dword v[192:193], v248, off offset:576
	s_or_b64 exec, exec, s[8:9]
	ds_bpermute_b32 v162, v223, v166
	ds_bpermute_b32 v163, v223, v167
	ds_bpermute_b32 v164, v223, v168
	ds_bpermute_b32 v165, v223, v169
	v_add_f32_e32 v243, v243, v249
	ds_bpermute_b32 v0, v224, v243
	s_waitcnt vmcnt(12)
; __device__ __forceinline__ float bf_lo(unsigned w) { return __uint_as_float(w << 16); }
; __device__ __forceinline__ float bf_hi(unsigned w) { return __uint_as_float(w & 0xffff0000u); }
; __device__ __forceinline__ float sigm(float v) { return __builtin_amdgcn_rcpf(1.0f + __builtin_amdgcn_exp2f(-1.44269504089f * v)); }
; __device__ __forceinline__ u32x4 pack8(const f32x4& v0, const f32x4& v1) { u32x4 w; w.x = cvt_pk_bf16(v0[0], v0[1]); w.y = cvt_pk_bf16(v0[2], v0[3]); w.z = cvt_pk_bf16(v1[0], v1[1]); w.w = cvt_pk_bf16(v1[2], v1[3]); return w; }
; __device__ __forceinline__ float sumsq8(const f32x4& v0, const f32x4& v1) { return (v0[0] * v0[0] + v0[1] * v0[1]) + (v0[2] * v0[2] + v0[3] * v0[3]) + (v1[0] * v1[0] + v1[1] * v1[1]) + (v1[2] * v1[2] + v1[3] * v1[3]); }
; __device__ __forceinline__ void epi_run(const Epi& E, f32x4 (&acc)[2][2][4][2], const Unit& u, int wr, int wc, int fr, int fq) {
;     ...
;                 for (int mm = 0; mm < 2; ++mm) { const int m = 2 * mh + mm, row = row0 + ai * 128 + m * 16; float sq = 0.f;
; #pragma unroll
;                     for (int bj = 0; bj < 2; ++bj) { const u32x4 xx = x[mm][bj], cc = c[mm][bj];
;                         const f32x4 c0 = (f32x4){bf_lo(cc.x), bf_hi(cc.x), bf_lo(cc.y), bf_hi(cc.y)}, c1 = (f32x4){bf_lo(cc.z), bf_hi(cc.z), bf_lo(cc.w), bf_hi(cc.w)};
;                         f32x4 v0 = acc[ai][bj][m][0] * rs[ai][m], v1 = acc[ai][bj][m][1] * rs[ai][m];
; #pragma unroll
;                         for (int e = 0; e < 4; ++e) { v0[e] = sigm(v0[e]) * c0[e]; v1[e] = sigm(v1[e]) * c1[e]; }
;                         const f32x4 x0 = (f32x4){bf_lo(xx.x), bf_hi(xx.x), bf_lo(xx.y), bf_hi(xx.y)} + v0, x1 = (f32x4){bf_lo(xx.z), bf_hi(xx.z), bf_lo(xx.w), bf_hi(xx.w)} + v1;
;                         sq += sumsq8(x0, x1); *(u32x4*)(E.xout16 + (size_t)row * D + col0 + bj * 128) = pack8(x0, x1); }
;                     sq += __shfl_xor(sq, 16); sq += __shfl_xor(sq, 32); if (fq == 0) sslot[row] = sq; }
	v_mov_b32_e32 v248, 0
	v_mov_b32_e32 v249, 0
	v_pk_mul_f32 v[170:171], v[14:15], v[220:221] op_sel:[0,1] op_sel_hi:[1,1]
	v_pk_mul_f32 v[172:173], v[16:17], v[220:221] op_sel:[0,1] op_sel_hi:[1,1]
	v_pk_mul_f32 v[174:175], v[10:11], v[220:221] op_sel:[0,1] op_sel_hi:[1,1]
	v_pk_mul_f32 v[176:177], v[12:13], v[220:221] op_sel:[0,1] op_sel_hi:[1,1]
	v_exp_f32_e32 v170, v170
	v_exp_f32_e32 v171, v171
	v_exp_f32_e32 v172, v172
	v_exp_f32_e32 v173, v173
	v_exp_f32_e32 v174, v174
	v_exp_f32_e32 v175, v175
	v_exp_f32_e32 v176, v176
	v_exp_f32_e32 v177, v177
	v_pk_add_f32 v[170:171], v[170:171], v[222:223] op_sel_hi:[1,0]
	v_pk_add_f32 v[172:173], v[172:173], v[222:223] op_sel_hi:[1,0]
	v_pk_add_f32 v[174:175], v[174:175], v[222:223] op_sel_hi:[1,0]
	v_pk_add_f32 v[176:177], v[176:177], v[222:223] op_sel_hi:[1,0]
	v_rcp_f32_e32 v170, v170
	v_rcp_f32_e32 v171, v171
	v_rcp_f32_e32 v172, v172
	v_rcp_f32_e32 v173, v173
	v_rcp_f32_e32 v174, v174
	v_rcp_f32_e32 v175, v175
	v_rcp_f32_e32 v176, v176
	v_rcp_f32_e32 v177, v177
	v_lshlrev_b32_e32 v178, 16, v122
	v_and_b32_e32 v179, 0xffff0000, v122
	v_lshlrev_b32_e32 v180, 16, v126
	v_and_b32_e32 v181, 0xffff0000, v126
	v_pk_fma_f32 v[170:171], v[170:171], v[178:179], v[180:181]
	v_lshlrev_b32_e32 v178, 16, v123
	v_and_b32_e32 v179, 0xffff0000, v123
	v_lshlrev_b32_e32 v180, 16, v127
	v_and_b32_e32 v181, 0xffff0000, v127
	v_pk_fma_f32 v[172:173], v[172:173], v[178:179], v[180:181]
	v_fmac_f32_e32 v248, v170, v170
	v_fmac_f32_e32 v249, v171, v171
	v_cvt_pk_bf16_f32 v166, v170, v171
	v_lshlrev_b32_e32 v178, 16, v124
	v_and_b32_e32 v179, 0xffff0000, v124
	v_lshlrev_b32_e32 v180, 16, v128
	v_and_b32_e32 v181, 0xffff0000, v128
	v_pk_fma_f32 v[174:175], v[174:175], v[178:179], v[180:181]
	v_fmac_f32_e32 v248, v172, v172
	v_fmac_f32_e32 v249, v173, v173
	v_cvt_pk_bf16_f32 v167, v172, v173
	v_lshlrev_b32_e32 v178, 16, v125
	v_and_b32_e32 v179, 0xffff0000, v125
	v_lshlrev_b32_e32 v180, 16, v129
	v_and_b32_e32 v181, 0xffff0000, v129
	v_pk_fma_f32 v[176:177], v[176:177], v[178:179], v[180:181]
	v_fmac_f32_e32 v248, v174, v174
	v_fmac_f32_e32 v249, v175, v175
	v_cvt_pk_bf16_f32 v168, v174, v175
	v_fmac_f32_e32 v248, v176, v176
	v_fmac_f32_e32 v249, v177, v177
	v_cvt_pk_bf16_f32 v169, v176, v177
	s_waitcnt lgkmcnt(0)
	global_store_dwordx4 v[228:229], v[162:165], off offset:256
	v_add_f32_e32 v243, v243, v0
	ds_bpermute_b32 v0, v225, v243
	s_mov_b64 s[20:21], 0x58000
	v_lshl_add_u64 v[230:231], v[186:187], 0, s[20:21]
	ds_bpermute_b32 v244, v223, v166
	ds_bpermute_b32 v245, v223, v167
	ds_bpermute_b32 v246, v223, v168
	ds_bpermute_b32 v247, v223, v169
	v_pk_mul_f32 v[170:171], v[6:7], v[220:221] op_sel:[0,1] op_sel_hi:[1,1]
	v_pk_mul_f32 v[172:173], v[8:9], v[220:221] op_sel:[0,1] op_sel_hi:[1,1]
	v_pk_mul_f32 v[174:175], v[2:3], v[220:221] op_sel:[0,1] op_sel_hi:[1,1]
	v_pk_mul_f32 v[176:177], v[4:5], v[220:221] op_sel:[0,1] op_sel_hi:[1,1]
	v_exp_f32_e32 v170, v170
	v_exp_f32_e32 v171, v171
	v_exp_f32_e32 v172, v172
	v_exp_f32_e32 v173, v173
	v_exp_f32_e32 v174, v174
	v_exp_f32_e32 v175, v175
	v_exp_f32_e32 v176, v176
	v_exp_f32_e32 v177, v177
	v_pk_add_f32 v[170:171], v[170:171], v[222:223] op_sel_hi:[1,0]
	v_pk_add_f32 v[172:173], v[172:173], v[222:223] op_sel_hi:[1,0]
	v_pk_add_f32 v[174:175], v[174:175], v[222:223] op_sel_hi:[1,0]
	v_pk_add_f32 v[176:177], v[176:177], v[222:223] op_sel_hi:[1,0]
	v_rcp_f32_e32 v170, v170
	v_rcp_f32_e32 v171, v171
	v_rcp_f32_e32 v172, v172
	v_rcp_f32_e32 v173, v173
	v_rcp_f32_e32 v174, v174
	v_rcp_f32_e32 v175, v175
	v_rcp_f32_e32 v176, v176
	v_rcp_f32_e32 v177, v177
	v_lshlrev_b32_e32 v178, 16, v114
	v_and_b32_e32 v179, 0xffff0000, v114
	v_lshlrev_b32_e32 v180, 16, v118
	v_and_b32_e32 v181, 0xffff0000, v118
	v_pk_fma_f32 v[170:171], v[170:171], v[178:179], v[180:181]
	v_lshlrev_b32_e32 v178, 16, v115
	v_and_b32_e32 v179, 0xffff0000, v115
	v_lshlrev_b32_e32 v180, 16, v119
	v_and_b32_e32 v181, 0xffff0000, v119
	v_pk_fma_f32 v[172:173], v[172:173], v[178:179], v[180:181]
	v_fmac_f32_e32 v248, v170, v170
	v_fmac_f32_e32 v249, v171, v171
	v_cvt_pk_bf16_f32 v166, v170, v171
	v_lshlrev_b32_e32 v178, 16, v116
	v_and_b32_e32 v179, 0xffff0000, v116
	v_lshlrev_b32_e32 v180, 16, v120
	v_and_b32_e32 v181, 0xffff0000, v120
	v_pk_fma_f32 v[174:175], v[174:175], v[178:179], v[180:181]
	v_fmac_f32_e32 v248, v172, v172
	v_fmac_f32_e32 v249, v173, v173
	v_cvt_pk_bf16_f32 v167, v172, v173
	v_lshlrev_b32_e32 v178, 16, v117
	v_and_b32_e32 v179, 0xffff0000, v117
	v_lshlrev_b32_e32 v180, 16, v121
	v_and_b32_e32 v181, 0xffff0000, v121
	v_pk_fma_f32 v[176:177], v[176:177], v[178:179], v[180:181]
	v_fmac_f32_e32 v248, v174, v174
	v_fmac_f32_e32 v249, v175, v175
	v_cvt_pk_bf16_f32 v168, v174, v175
	v_fmac_f32_e32 v248, v176, v176
	v_fmac_f32_e32 v249, v177, v177
	v_cvt_pk_bf16_f32 v169, v176, v177
	s_waitcnt lgkmcnt(0)
	global_store_dwordx4 v[230:231], v[244:247], off
	v_add_f32_e32 v243, v243, v0
	s_and_saveexec_b64 s[8:9], s[40:41]
	global_store_dword v[192:193], v243, off offset:640
	s_or_b64 exec, exec, s[8:9]
	ds_bpermute_b32 v162, v223, v166
	ds_bpermute_b32 v163, v223, v167
	ds_bpermute_b32 v164, v223, v168
	ds_bpermute_b32 v165, v223, v169
	v_add_f32_e32 v248, v248, v249
	ds_bpermute_b32 v0, v224, v248
	s_waitcnt lgkmcnt(0)
	global_store_dwordx4 v[230:231], v[162:165], off offset:256
	v_add_f32_e32 v248, v248, v0
	ds_bpermute_b32 v0, v225, v248
	s_waitcnt lgkmcnt(0)
	v_add_f32_e32 v248, v248, v0
	s_and_saveexec_b64 s[8:9], s[40:41]
	global_store_dword v[192:193], v248, off offset:704
	s_or_b64 exec, exec, s[8:9]
	s_mov_b64 s[44:45], 0
